# P1 row loop rewritten: fully unrolled, 4 x-rows in flight per wave, modulation vectors loaded once per batch (double buffered), nt on x loads and XN stores; plus tailnt+gmlpnt
# speedup vs baseline: 1.0064x; 1.0064x over previous
.LBB0_75:
	v_writelane_b32 v253, s70, 21
	s_cmp_lt_i32 s94, 2
	s_nop 0
	v_writelane_b32 v253, s71, 22
	s_load_dwordx16 s[60:75], s[0:1], 0x40
	s_cselect_b64 s[0:1], -1, 0
	s_add_u32 s2, s44, 0x200000
	s_addc_u32 s3, s45, 0
	v_writelane_b32 v253, s2, 23
	s_nop 1
	v_writelane_b32 v253, s3, 24
	s_add_u32 s2, s44, 0x1e00000
	s_addc_u32 s3, s45, 0
	v_writelane_b32 v253, s2, 25
	s_nop 1
	v_writelane_b32 v253, s3, 26
	s_add_u32 s2, s44, 0x130000
	s_addc_u32 s3, s45, 0
	v_writelane_b32 v253, s2, 27
	s_and_b64 s[12:13], s[0:1], s[4:5]
	s_mov_b32 s0, s78
	v_writelane_b32 v253, s3, 28
	v_writelane_b32 v253, s44, 29
	s_andn2_b64 vcc, exec, s[12:13]
	s_nop 0
	v_writelane_b32 v253, s45, 30
	v_writelane_b32 v253, s76, 31
	v_writelane_b32 v253, s0, 32
	s_nop 1
	v_writelane_b32 v253, s1, 33
	s_cbranch_vccnz .LBB0_112
	s_mov_b32 s0, s54
	s_lshl_b32 s0, s0, 3
	s_mov_b64 s[52:53], s[80:81]
	s_add_i32 s4, s0, s78
	s_mov_b64 s[54:55], s[82:83]
	s_mov_b64 s[56:57], s[84:85]
	s_mov_b64 s[58:59], s[86:87]
	s_cmp_gt_i32 s4, 0x83ff
	s_cbranch_scc1 .LBB0_81
	v_readlane_b32 s76, v253, 4
	v_readlane_b32 s77, v253, 5
	v_readlane_b32 s80, v253, 8
	v_readlane_b32 s81, v253, 9
	v_readlane_b32 s28, v253, 16
	v_readlane_b32 s29, v253, 17
	v_lshlrev_b32_e32 v1, 4, v218
	v_lshlrev_b32_e32 v2, 3, v218
	v_lshlrev_b32_e32 v3, 2, v218
	v_mov_b32_e32 v204, 0x358637bd
	s_add_u32 s8, s44, 0x100000
	s_addc_u32 s9, s45, 0
	s_add_u32 s10, s44, 0x2200000
	s_addc_u32 s11, s45, 0
	s_add_u32 s14, s44, 0x15600000
	s_addc_u32 s15, s45, 0
	s_lshl_b32 s0, s4, 12
	s_add_u32 s20, s76, s0
	s_addc_u32 s21, s77, 0
	s_add_u32 s30, s80, s0
	s_addc_u32 s31, s81, 0
	s_lshl_b32 s0, s4, 11
	s_add_u32 s16, s10, s0
	s_addc_u32 s17, s11, 0
	s_lshl_b32 s0, s4, 10
	s_add_u32 s18, s14, s0
	s_addc_u32 s19, s15, 0
	global_load_dwordx4 v[172:175], v1, s[28:29]
	global_load_dwordx4 v[176:179], v1, s[28:29] offset:1024
	global_load_dwordx4 v[180:183], v1, s[28:29] offset:2048
	global_load_dwordx4 v[184:187], v1, s[28:29] offset:3072
	global_load_dwordx4 v[4:7], v1, s[20:21] nt
	global_load_dwordx4 v[8:11], v1, s[20:21] offset:1024 nt
	global_load_dwordx4 v[12:15], v1, s[20:21] offset:2048 nt
	global_load_dwordx4 v[16:19], v1, s[20:21] offset:3072 nt
	s_add_u32 s20, s20, 0x800000
	s_addc_u32 s21, s21, 0
	s_add_u32 s22, s8, 0x0
	s_addc_u32 s23, s9, 0
	s_add_u32 s24, s22, 0x1000
	s_addc_u32 s25, s23, 0
	global_load_dwordx4 v[220:223], v1, s[24:25]
	global_load_dwordx4 v[224:227], v1, s[24:25] offset:1024
	global_load_dwordx4 v[228:231], v1, s[24:25] offset:2048
	global_load_dwordx4 v[232:235], v1, s[24:25] offset:3072
	global_load_dwordx4 v[236:239], v1, s[22:23]
	global_load_dwordx4 v[240:243], v1, s[22:23] offset:1024
	global_load_dwordx4 v[244:247], v1, s[22:23] offset:2048
	global_load_dwordx4 v[248:251], v1, s[22:23] offset:3072
	global_load_dwordx4 v[20:23], v1, s[20:21] nt
	global_load_dwordx4 v[24:27], v1, s[20:21] offset:1024 nt
	global_load_dwordx4 v[28:31], v1, s[20:21] offset:2048 nt
	global_load_dwordx4 v[32:35], v1, s[20:21] offset:3072 nt
	s_add_u32 s20, s20, 0x800000
	s_addc_u32 s21, s21, 0
	s_add_u32 s22, s8, 0x6000
	s_addc_u32 s23, s9, 0
	s_add_u32 s24, s22, 0x1000
	s_addc_u32 s25, s23, 0
	global_load_dwordx4 v[58:61], v1, s[24:25]
	global_load_dwordx4 v[62:65], v1, s[24:25] offset:1024
	global_load_dwordx4 v[66:69], v1, s[24:25] offset:2048
	global_load_dwordx4 v[70:73], v1, s[24:25] offset:3072
	global_load_dwordx4 v[74:77], v1, s[22:23]
	global_load_dwordx4 v[78:81], v1, s[22:23] offset:1024
	global_load_dwordx4 v[82:85], v1, s[22:23] offset:2048
	global_load_dwordx4 v[86:89], v1, s[22:23] offset:3072
	global_load_dwordx4 v[36:39], v1, s[20:21] nt
	global_load_dwordx4 v[40:43], v1, s[20:21] offset:1024 nt
	global_load_dwordx4 v[44:47], v1, s[20:21] offset:2048 nt
	global_load_dwordx4 v[48:51], v1, s[20:21] offset:3072 nt
	s_add_u32 s20, s20, 0x800000
	s_addc_u32 s21, s21, 0
	global_load_dwordx4 v[188:191], v1, s[20:21] nt
	global_load_dwordx4 v[192:195], v1, s[20:21] offset:1024 nt
	global_load_dwordx4 v[196:199], v1, s[20:21] offset:2048 nt
	global_load_dwordx4 v[200:203], v1, s[20:21] offset:3072 nt
	s_add_u32 s20, s20, 0x800000
	s_addc_u32 s21, s21, 0
	s_waitcnt vmcnt(20)
	v_pk_mul_f32 v[54:55], v[4:5], v[4:5]
	v_pk_mul_f32 v[56:57], v[6:7], v[6:7]
	v_pk_fma_f32 v[54:55], v[8:9], v[8:9], v[54:55]
	v_pk_fma_f32 v[56:57], v[10:11], v[10:11], v[56:57]
	v_pk_fma_f32 v[54:55], v[12:13], v[12:13], v[54:55]
	v_pk_fma_f32 v[56:57], v[14:15], v[14:15], v[56:57]
	v_pk_fma_f32 v[54:55], v[16:17], v[16:17], v[54:55]
	v_pk_fma_f32 v[56:57], v[18:19], v[18:19], v[56:57]
	v_pk_add_f32 v[54:55], v[54:55], v[56:57]
	s_nop 0
	v_add_f32_e32 v52, v54, v55
	s_nop 1
	v_add_f32_dpp v52, v52, v52 quad_perm:[1,0,3,2] row_mask:0xf bank_mask:0xf
	s_nop 1
	v_add_f32_dpp v52, v52, v52 quad_perm:[2,3,0,1] row_mask:0xf bank_mask:0xf
	s_nop 1
	v_add_f32_dpp v52, v52, v52 row_half_mirror row_mask:0xf bank_mask:0xf
	s_nop 1
	v_add_f32_dpp v52, v52, v52 row_mirror row_mask:0xf bank_mask:0xf
	s_nop 1
	v_add_f32_dpp v52, v52, v52 row_bcast:15 row_mask:0xa bank_mask:0xf
	s_nop 1
	v_add_f32_dpp v52, v52, v52 row_bcast:31 row_mask:0xc bank_mask:0xf
	s_nop 1
	v_readlane_b32 s27, v52, 63
	s_nop 3
	v_mov_b32_e32 v52, s27
	v_fmamk_f32 v52, v52, 0x3a800000, v204
	v_rsq_f32_e32 v52, v52
	s_nop 1
	v_pk_mul_f32 v[4:5], v[4:5], v[52:53] op_sel_hi:[1,0]
	v_pk_mul_f32 v[6:7], v[6:7], v[52:53] op_sel_hi:[1,0]
	v_pk_mul_f32 v[8:9], v[8:9], v[52:53] op_sel_hi:[1,0]
	v_pk_mul_f32 v[10:11], v[10:11], v[52:53] op_sel_hi:[1,0]
	v_pk_mul_f32 v[12:13], v[12:13], v[52:53] op_sel_hi:[1,0]
	v_pk_mul_f32 v[14:15], v[14:15], v[52:53] op_sel_hi:[1,0]
	v_pk_mul_f32 v[16:17], v[16:17], v[52:53] op_sel_hi:[1,0]
	v_pk_mul_f32 v[18:19], v[18:19], v[52:53] op_sel_hi:[1,0]
	v_pk_mul_f32 v[4:5], v[172:173], v[4:5]
	v_pk_mul_f32 v[6:7], v[174:175], v[6:7]
	v_pk_mul_f32 v[8:9], v[176:177], v[8:9]
	v_pk_mul_f32 v[10:11], v[178:179], v[10:11]
	v_pk_mul_f32 v[12:13], v[180:181], v[12:13]
	v_pk_mul_f32 v[14:15], v[182:183], v[14:15]
	v_pk_mul_f32 v[16:17], v[184:185], v[16:17]
	v_pk_mul_f32 v[18:19], v[186:187], v[18:19]
	v_pk_add_f32 v[56:57], v[220:221], 1.0 op_sel_hi:[1,0]
	v_pk_fma_f32 v[4:5], v[56:57], v[4:5], v[236:237]
	v_pk_add_f32 v[56:57], v[222:223], 1.0 op_sel_hi:[1,0]
	v_pk_fma_f32 v[6:7], v[56:57], v[6:7], v[238:239]
	v_pk_add_f32 v[56:57], v[224:225], 1.0 op_sel_hi:[1,0]
	v_pk_fma_f32 v[8:9], v[56:57], v[8:9], v[240:241]
	v_pk_add_f32 v[56:57], v[226:227], 1.0 op_sel_hi:[1,0]
	v_pk_fma_f32 v[10:11], v[56:57], v[10:11], v[242:243]
	v_pk_add_f32 v[56:57], v[228:229], 1.0 op_sel_hi:[1,0]
	v_pk_fma_f32 v[12:13], v[56:57], v[12:13], v[244:245]
	v_pk_add_f32 v[56:57], v[230:231], 1.0 op_sel_hi:[1,0]
	v_pk_fma_f32 v[14:15], v[56:57], v[14:15], v[246:247]
	v_pk_add_f32 v[56:57], v[232:233], 1.0 op_sel_hi:[1,0]
	v_pk_fma_f32 v[16:17], v[56:57], v[16:17], v[248:249]
	v_pk_add_f32 v[56:57], v[234:235], 1.0 op_sel_hi:[1,0]
	v_pk_fma_f32 v[18:19], v[56:57], v[18:19], v[250:251]
	v_cvt_pk_bf16_f32 v206, v4, v5
	v_cvt_pk_bf16_f32 v207, v6, v7
	v_cvt_pk_fp8_f32 v214, v4, v5
	v_cvt_pk_bf16_f32 v208, v8, v9
	v_cvt_pk_bf16_f32 v209, v10, v11
	v_cvt_pk_fp8_f32 v215, v8, v9
	v_cvt_pk_bf16_f32 v210, v12, v13
	v_cvt_pk_bf16_f32 v211, v14, v15
	v_cvt_pk_fp8_f32 v216, v12, v13
	v_cvt_pk_bf16_f32 v212, v16, v17
	v_cvt_pk_bf16_f32 v213, v18, v19
	v_cvt_pk_fp8_f32 v217, v16, v17
	v_cvt_pk_fp8_f32 v214, v6, v7 op_sel:[0,0,1]
	v_cvt_pk_fp8_f32 v215, v10, v11 op_sel:[0,0,1]
	v_cvt_pk_fp8_f32 v216, v14, v15 op_sel:[0,0,1]
	v_cvt_pk_fp8_f32 v217, v18, v19 op_sel:[0,0,1]
	s_nop 1
	global_store_dwordx2 v2, v[206:207], s[16:17] nt
	global_store_dwordx2 v2, v[208:209], s[16:17] offset:512 nt
	global_store_dwordx2 v2, v[210:211], s[16:17] offset:1024 nt
	global_store_dwordx2 v2, v[212:213], s[16:17] offset:1536 nt
	global_store_dword v3, v214, s[18:19] nt
	global_store_dword v3, v215, s[18:19] offset:256 nt
	global_store_dword v3, v216, s[18:19] offset:512 nt
	global_store_dword v3, v217, s[18:19] offset:768 nt
	s_add_u32 s16, s16, 0x400000
	s_addc_u32 s17, s17, 0
	s_add_u32 s18, s18, 0x200000
	s_addc_u32 s19, s19, 0
	global_load_dwordx4 v[4:7], v1, s[20:21] nt
	global_load_dwordx4 v[8:11], v1, s[20:21] offset:1024 nt
	global_load_dwordx4 v[12:15], v1, s[20:21] offset:2048 nt
	global_load_dwordx4 v[16:19], v1, s[20:21] offset:3072 nt
	s_add_u32 s20, s20, 0x800000
	s_addc_u32 s21, s21, 0
	s_waitcnt vmcnt(28)
	v_pk_mul_f32 v[54:55], v[20:21], v[20:21]
	v_pk_mul_f32 v[56:57], v[22:23], v[22:23]
	v_pk_fma_f32 v[54:55], v[24:25], v[24:25], v[54:55]
	v_pk_fma_f32 v[56:57], v[26:27], v[26:27], v[56:57]
	v_pk_fma_f32 v[54:55], v[28:29], v[28:29], v[54:55]
	v_pk_fma_f32 v[56:57], v[30:31], v[30:31], v[56:57]
	v_pk_fma_f32 v[54:55], v[32:33], v[32:33], v[54:55]
	v_pk_fma_f32 v[56:57], v[34:35], v[34:35], v[56:57]
	v_pk_add_f32 v[54:55], v[54:55], v[56:57]
	s_nop 0
	v_add_f32_e32 v52, v54, v55
	s_nop 1
	v_add_f32_dpp v52, v52, v52 quad_perm:[1,0,3,2] row_mask:0xf bank_mask:0xf
	s_nop 1
	v_add_f32_dpp v52, v52, v52 quad_perm:[2,3,0,1] row_mask:0xf bank_mask:0xf
	s_nop 1
	v_add_f32_dpp v52, v52, v52 row_half_mirror row_mask:0xf bank_mask:0xf
	s_nop 1
	v_add_f32_dpp v52, v52, v52 row_mirror row_mask:0xf bank_mask:0xf
	s_nop 1
	v_add_f32_dpp v52, v52, v52 row_bcast:15 row_mask:0xa bank_mask:0xf
	s_nop 1
	v_add_f32_dpp v52, v52, v52 row_bcast:31 row_mask:0xc bank_mask:0xf
	s_nop 1
	v_readlane_b32 s27, v52, 63
	s_nop 3
	v_mov_b32_e32 v52, s27
	v_fmamk_f32 v52, v52, 0x3a800000, v204
	v_rsq_f32_e32 v52, v52
	s_nop 1
	v_pk_mul_f32 v[20:21], v[20:21], v[52:53] op_sel_hi:[1,0]
	v_pk_mul_f32 v[22:23], v[22:23], v[52:53] op_sel_hi:[1,0]
	v_pk_mul_f32 v[24:25], v[24:25], v[52:53] op_sel_hi:[1,0]
	v_pk_mul_f32 v[26:27], v[26:27], v[52:53] op_sel_hi:[1,0]
	v_pk_mul_f32 v[28:29], v[28:29], v[52:53] op_sel_hi:[1,0]
	v_pk_mul_f32 v[30:31], v[30:31], v[52:53] op_sel_hi:[1,0]
	v_pk_mul_f32 v[32:33], v[32:33], v[52:53] op_sel_hi:[1,0]
	v_pk_mul_f32 v[34:35], v[34:35], v[52:53] op_sel_hi:[1,0]
	v_pk_mul_f32 v[20:21], v[172:173], v[20:21]
	v_pk_mul_f32 v[22:23], v[174:175], v[22:23]
	v_pk_mul_f32 v[24:25], v[176:177], v[24:25]
	v_pk_mul_f32 v[26:27], v[178:179], v[26:27]
	v_pk_mul_f32 v[28:29], v[180:181], v[28:29]
	v_pk_mul_f32 v[30:31], v[182:183], v[30:31]
	v_pk_mul_f32 v[32:33], v[184:185], v[32:33]
	v_pk_mul_f32 v[34:35], v[186:187], v[34:35]
	v_pk_add_f32 v[56:57], v[220:221], 1.0 op_sel_hi:[1,0]
	v_pk_fma_f32 v[20:21], v[56:57], v[20:21], v[236:237]
	v_pk_add_f32 v[56:57], v[222:223], 1.0 op_sel_hi:[1,0]
	v_pk_fma_f32 v[22:23], v[56:57], v[22:23], v[238:239]
	v_pk_add_f32 v[56:57], v[224:225], 1.0 op_sel_hi:[1,0]
	v_pk_fma_f32 v[24:25], v[56:57], v[24:25], v[240:241]
	v_pk_add_f32 v[56:57], v[226:227], 1.0 op_sel_hi:[1,0]
	v_pk_fma_f32 v[26:27], v[56:57], v[26:27], v[242:243]
	v_pk_add_f32 v[56:57], v[228:229], 1.0 op_sel_hi:[1,0]
	v_pk_fma_f32 v[28:29], v[56:57], v[28:29], v[244:245]
	v_pk_add_f32 v[56:57], v[230:231], 1.0 op_sel_hi:[1,0]
	v_pk_fma_f32 v[30:31], v[56:57], v[30:31], v[246:247]
	v_pk_add_f32 v[56:57], v[232:233], 1.0 op_sel_hi:[1,0]
	v_pk_fma_f32 v[32:33], v[56:57], v[32:33], v[248:249]
	v_pk_add_f32 v[56:57], v[234:235], 1.0 op_sel_hi:[1,0]
	v_pk_fma_f32 v[34:35], v[56:57], v[34:35], v[250:251]
	v_cvt_pk_bf16_f32 v206, v20, v21
	v_cvt_pk_bf16_f32 v207, v22, v23
	v_cvt_pk_fp8_f32 v214, v20, v21
	v_cvt_pk_bf16_f32 v208, v24, v25
	v_cvt_pk_bf16_f32 v209, v26, v27
	v_cvt_pk_fp8_f32 v215, v24, v25
	v_cvt_pk_bf16_f32 v210, v28, v29
	v_cvt_pk_bf16_f32 v211, v30, v31
	v_cvt_pk_fp8_f32 v216, v28, v29
	v_cvt_pk_bf16_f32 v212, v32, v33
	v_cvt_pk_bf16_f32 v213, v34, v35
	v_cvt_pk_fp8_f32 v217, v32, v33
	v_cvt_pk_fp8_f32 v214, v22, v23 op_sel:[0,0,1]
	v_cvt_pk_fp8_f32 v215, v26, v27 op_sel:[0,0,1]
	v_cvt_pk_fp8_f32 v216, v30, v31 op_sel:[0,0,1]
	v_cvt_pk_fp8_f32 v217, v34, v35 op_sel:[0,0,1]
	s_nop 1
	global_store_dwordx2 v2, v[206:207], s[16:17] nt
	global_store_dwordx2 v2, v[208:209], s[16:17] offset:512 nt
	global_store_dwordx2 v2, v[210:211], s[16:17] offset:1024 nt
	global_store_dwordx2 v2, v[212:213], s[16:17] offset:1536 nt
	global_store_dword v3, v214, s[18:19] nt
	global_store_dword v3, v215, s[18:19] offset:256 nt
	global_store_dword v3, v216, s[18:19] offset:512 nt
	global_store_dword v3, v217, s[18:19] offset:768 nt
	s_add_u32 s16, s16, 0x400000
	s_addc_u32 s17, s17, 0
	s_add_u32 s18, s18, 0x200000
	s_addc_u32 s19, s19, 0
	global_load_dwordx4 v[20:23], v1, s[20:21] nt
	global_load_dwordx4 v[24:27], v1, s[20:21] offset:1024 nt
	global_load_dwordx4 v[28:31], v1, s[20:21] offset:2048 nt
	global_load_dwordx4 v[32:35], v1, s[20:21] offset:3072 nt
	s_add_u32 s20, s20, 0x800000
	s_addc_u32 s21, s21, 0
	s_waitcnt vmcnt(28)
	v_pk_mul_f32 v[54:55], v[36:37], v[36:37]
	v_pk_mul_f32 v[56:57], v[38:39], v[38:39]
	v_pk_fma_f32 v[54:55], v[40:41], v[40:41], v[54:55]
	v_pk_fma_f32 v[56:57], v[42:43], v[42:43], v[56:57]
	v_pk_fma_f32 v[54:55], v[44:45], v[44:45], v[54:55]
	v_pk_fma_f32 v[56:57], v[46:47], v[46:47], v[56:57]
	v_pk_fma_f32 v[54:55], v[48:49], v[48:49], v[54:55]
	v_pk_fma_f32 v[56:57], v[50:51], v[50:51], v[56:57]
	v_pk_add_f32 v[54:55], v[54:55], v[56:57]
	s_nop 0
	v_add_f32_e32 v52, v54, v55
	s_nop 1
	v_add_f32_dpp v52, v52, v52 quad_perm:[1,0,3,2] row_mask:0xf bank_mask:0xf
	s_nop 1
	v_add_f32_dpp v52, v52, v52 quad_perm:[2,3,0,1] row_mask:0xf bank_mask:0xf
	s_nop 1
	v_add_f32_dpp v52, v52, v52 row_half_mirror row_mask:0xf bank_mask:0xf
	s_nop 1
	v_add_f32_dpp v52, v52, v52 row_mirror row_mask:0xf bank_mask:0xf
	s_nop 1
	v_add_f32_dpp v52, v52, v52 row_bcast:15 row_mask:0xa bank_mask:0xf
	s_nop 1
	v_add_f32_dpp v52, v52, v52 row_bcast:31 row_mask:0xc bank_mask:0xf
	s_nop 1
	v_readlane_b32 s27, v52, 63
	s_nop 3
	v_mov_b32_e32 v52, s27
	v_fmamk_f32 v52, v52, 0x3a800000, v204
	v_rsq_f32_e32 v52, v52
	s_nop 1
	v_pk_mul_f32 v[36:37], v[36:37], v[52:53] op_sel_hi:[1,0]
	v_pk_mul_f32 v[38:39], v[38:39], v[52:53] op_sel_hi:[1,0]
	v_pk_mul_f32 v[40:41], v[40:41], v[52:53] op_sel_hi:[1,0]
	v_pk_mul_f32 v[42:43], v[42:43], v[52:53] op_sel_hi:[1,0]
	v_pk_mul_f32 v[44:45], v[44:45], v[52:53] op_sel_hi:[1,0]
	v_pk_mul_f32 v[46:47], v[46:47], v[52:53] op_sel_hi:[1,0]
	v_pk_mul_f32 v[48:49], v[48:49], v[52:53] op_sel_hi:[1,0]
	v_pk_mul_f32 v[50:51], v[50:51], v[52:53] op_sel_hi:[1,0]
	v_pk_mul_f32 v[36:37], v[172:173], v[36:37]
	v_pk_mul_f32 v[38:39], v[174:175], v[38:39]
	v_pk_mul_f32 v[40:41], v[176:177], v[40:41]
	v_pk_mul_f32 v[42:43], v[178:179], v[42:43]
	v_pk_mul_f32 v[44:45], v[180:181], v[44:45]
	v_pk_mul_f32 v[46:47], v[182:183], v[46:47]
	v_pk_mul_f32 v[48:49], v[184:185], v[48:49]
	v_pk_mul_f32 v[50:51], v[186:187], v[50:51]
	v_pk_add_f32 v[56:57], v[220:221], 1.0 op_sel_hi:[1,0]
	v_pk_fma_f32 v[36:37], v[56:57], v[36:37], v[236:237]
	v_pk_add_f32 v[56:57], v[222:223], 1.0 op_sel_hi:[1,0]
	v_pk_fma_f32 v[38:39], v[56:57], v[38:39], v[238:239]
	v_pk_add_f32 v[56:57], v[224:225], 1.0 op_sel_hi:[1,0]
	v_pk_fma_f32 v[40:41], v[56:57], v[40:41], v[240:241]
	v_pk_add_f32 v[56:57], v[226:227], 1.0 op_sel_hi:[1,0]
	v_pk_fma_f32 v[42:43], v[56:57], v[42:43], v[242:243]
	v_pk_add_f32 v[56:57], v[228:229], 1.0 op_sel_hi:[1,0]
	v_pk_fma_f32 v[44:45], v[56:57], v[44:45], v[244:245]
	v_pk_add_f32 v[56:57], v[230:231], 1.0 op_sel_hi:[1,0]
	v_pk_fma_f32 v[46:47], v[56:57], v[46:47], v[246:247]
	v_pk_add_f32 v[56:57], v[232:233], 1.0 op_sel_hi:[1,0]
	v_pk_fma_f32 v[48:49], v[56:57], v[48:49], v[248:249]
	v_pk_add_f32 v[56:57], v[234:235], 1.0 op_sel_hi:[1,0]
	v_pk_fma_f32 v[50:51], v[56:57], v[50:51], v[250:251]
	v_cvt_pk_bf16_f32 v206, v36, v37
	v_cvt_pk_bf16_f32 v207, v38, v39
	v_cvt_pk_fp8_f32 v214, v36, v37
	v_cvt_pk_bf16_f32 v208, v40, v41
	v_cvt_pk_bf16_f32 v209, v42, v43
	v_cvt_pk_fp8_f32 v215, v40, v41
	v_cvt_pk_bf16_f32 v210, v44, v45
	v_cvt_pk_bf16_f32 v211, v46, v47
	v_cvt_pk_fp8_f32 v216, v44, v45
	v_cvt_pk_bf16_f32 v212, v48, v49
	v_cvt_pk_bf16_f32 v213, v50, v51
	v_cvt_pk_fp8_f32 v217, v48, v49
	v_cvt_pk_fp8_f32 v214, v38, v39 op_sel:[0,0,1]
	v_cvt_pk_fp8_f32 v215, v42, v43 op_sel:[0,0,1]
	v_cvt_pk_fp8_f32 v216, v46, v47 op_sel:[0,0,1]
	v_cvt_pk_fp8_f32 v217, v50, v51 op_sel:[0,0,1]
	s_nop 1
	global_store_dwordx2 v2, v[206:207], s[16:17] nt
	global_store_dwordx2 v2, v[208:209], s[16:17] offset:512 nt
	global_store_dwordx2 v2, v[210:211], s[16:17] offset:1024 nt
	global_store_dwordx2 v2, v[212:213], s[16:17] offset:1536 nt
	global_store_dword v3, v214, s[18:19] nt
	global_store_dword v3, v215, s[18:19] offset:256 nt
	global_store_dword v3, v216, s[18:19] offset:512 nt
	global_store_dword v3, v217, s[18:19] offset:768 nt
	s_add_u32 s16, s16, 0x400000
	s_addc_u32 s17, s17, 0
	s_add_u32 s18, s18, 0x200000
	s_addc_u32 s19, s19, 0
	global_load_dwordx4 v[36:39], v1, s[20:21] nt
	global_load_dwordx4 v[40:43], v1, s[20:21] offset:1024 nt
	global_load_dwordx4 v[44:47], v1, s[20:21] offset:2048 nt
	global_load_dwordx4 v[48:51], v1, s[20:21] offset:3072 nt
	s_add_u32 s20, s20, 0x800000
	s_addc_u32 s21, s21, 0
	s_waitcnt vmcnt(36)
	v_pk_mul_f32 v[54:55], v[188:189], v[188:189]
	v_pk_mul_f32 v[56:57], v[190:191], v[190:191]
	v_pk_fma_f32 v[54:55], v[192:193], v[192:193], v[54:55]
	v_pk_fma_f32 v[56:57], v[194:195], v[194:195], v[56:57]
	v_pk_fma_f32 v[54:55], v[196:197], v[196:197], v[54:55]
	v_pk_fma_f32 v[56:57], v[198:199], v[198:199], v[56:57]
	v_pk_fma_f32 v[54:55], v[200:201], v[200:201], v[54:55]
	v_pk_fma_f32 v[56:57], v[202:203], v[202:203], v[56:57]
	v_pk_add_f32 v[54:55], v[54:55], v[56:57]
	s_nop 0
	v_add_f32_e32 v52, v54, v55
	s_nop 1
	v_add_f32_dpp v52, v52, v52 quad_perm:[1,0,3,2] row_mask:0xf bank_mask:0xf
	s_nop 1
	v_add_f32_dpp v52, v52, v52 quad_perm:[2,3,0,1] row_mask:0xf bank_mask:0xf
	s_nop 1
	v_add_f32_dpp v52, v52, v52 row_half_mirror row_mask:0xf bank_mask:0xf
	s_nop 1
	v_add_f32_dpp v52, v52, v52 row_mirror row_mask:0xf bank_mask:0xf
	s_nop 1
	v_add_f32_dpp v52, v52, v52 row_bcast:15 row_mask:0xa bank_mask:0xf
	s_nop 1
	v_add_f32_dpp v52, v52, v52 row_bcast:31 row_mask:0xc bank_mask:0xf
	s_nop 1
	v_readlane_b32 s27, v52, 63
	s_nop 3
	v_mov_b32_e32 v52, s27
	v_fmamk_f32 v52, v52, 0x3a800000, v204
	v_rsq_f32_e32 v52, v52
	s_nop 1
	v_pk_mul_f32 v[188:189], v[188:189], v[52:53] op_sel_hi:[1,0]
	v_pk_mul_f32 v[190:191], v[190:191], v[52:53] op_sel_hi:[1,0]
	v_pk_mul_f32 v[192:193], v[192:193], v[52:53] op_sel_hi:[1,0]
	v_pk_mul_f32 v[194:195], v[194:195], v[52:53] op_sel_hi:[1,0]
	v_pk_mul_f32 v[196:197], v[196:197], v[52:53] op_sel_hi:[1,0]
	v_pk_mul_f32 v[198:199], v[198:199], v[52:53] op_sel_hi:[1,0]
	v_pk_mul_f32 v[200:201], v[200:201], v[52:53] op_sel_hi:[1,0]
	v_pk_mul_f32 v[202:203], v[202:203], v[52:53] op_sel_hi:[1,0]
	v_pk_mul_f32 v[188:189], v[172:173], v[188:189]
	v_pk_mul_f32 v[190:191], v[174:175], v[190:191]
	v_pk_mul_f32 v[192:193], v[176:177], v[192:193]
	v_pk_mul_f32 v[194:195], v[178:179], v[194:195]
	v_pk_mul_f32 v[196:197], v[180:181], v[196:197]
	v_pk_mul_f32 v[198:199], v[182:183], v[198:199]
	v_pk_mul_f32 v[200:201], v[184:185], v[200:201]
	v_pk_mul_f32 v[202:203], v[186:187], v[202:203]
	v_pk_add_f32 v[56:57], v[220:221], 1.0 op_sel_hi:[1,0]
	v_pk_fma_f32 v[188:189], v[56:57], v[188:189], v[236:237]
	v_pk_add_f32 v[56:57], v[222:223], 1.0 op_sel_hi:[1,0]
	v_pk_fma_f32 v[190:191], v[56:57], v[190:191], v[238:239]
	v_pk_add_f32 v[56:57], v[224:225], 1.0 op_sel_hi:[1,0]
	v_pk_fma_f32 v[192:193], v[56:57], v[192:193], v[240:241]
	v_pk_add_f32 v[56:57], v[226:227], 1.0 op_sel_hi:[1,0]
	v_pk_fma_f32 v[194:195], v[56:57], v[194:195], v[242:243]
	v_pk_add_f32 v[56:57], v[228:229], 1.0 op_sel_hi:[1,0]
	v_pk_fma_f32 v[196:197], v[56:57], v[196:197], v[244:245]
	v_pk_add_f32 v[56:57], v[230:231], 1.0 op_sel_hi:[1,0]
	v_pk_fma_f32 v[198:199], v[56:57], v[198:199], v[246:247]
	v_pk_add_f32 v[56:57], v[232:233], 1.0 op_sel_hi:[1,0]
	v_pk_fma_f32 v[200:201], v[56:57], v[200:201], v[248:249]
	v_pk_add_f32 v[56:57], v[234:235], 1.0 op_sel_hi:[1,0]
	v_pk_fma_f32 v[202:203], v[56:57], v[202:203], v[250:251]
	s_add_u32 s22, s8, 0xc000
	s_addc_u32 s23, s9, 0
	s_add_u32 s24, s22, 0x1000
	s_addc_u32 s25, s23, 0
	global_load_dwordx4 v[220:223], v1, s[24:25]
	global_load_dwordx4 v[224:227], v1, s[24:25] offset:1024
	global_load_dwordx4 v[228:231], v1, s[24:25] offset:2048
	global_load_dwordx4 v[232:235], v1, s[24:25] offset:3072
	global_load_dwordx4 v[236:239], v1, s[22:23]
	global_load_dwordx4 v[240:243], v1, s[22:23] offset:1024
	global_load_dwordx4 v[244:247], v1, s[22:23] offset:2048
	global_load_dwordx4 v[248:251], v1, s[22:23] offset:3072
	v_cvt_pk_bf16_f32 v206, v188, v189
	v_cvt_pk_bf16_f32 v207, v190, v191
	v_cvt_pk_fp8_f32 v214, v188, v189
	v_cvt_pk_bf16_f32 v208, v192, v193
	v_cvt_pk_bf16_f32 v209, v194, v195
	v_cvt_pk_fp8_f32 v215, v192, v193
	v_cvt_pk_bf16_f32 v210, v196, v197
	v_cvt_pk_bf16_f32 v211, v198, v199
	v_cvt_pk_fp8_f32 v216, v196, v197
	v_cvt_pk_bf16_f32 v212, v200, v201
	v_cvt_pk_bf16_f32 v213, v202, v203
	v_cvt_pk_fp8_f32 v217, v200, v201
	v_cvt_pk_fp8_f32 v214, v190, v191 op_sel:[0,0,1]
	v_cvt_pk_fp8_f32 v215, v194, v195 op_sel:[0,0,1]
	v_cvt_pk_fp8_f32 v216, v198, v199 op_sel:[0,0,1]
	v_cvt_pk_fp8_f32 v217, v202, v203 op_sel:[0,0,1]
	s_nop 1
	global_store_dwordx2 v2, v[206:207], s[16:17] nt
	global_store_dwordx2 v2, v[208:209], s[16:17] offset:512 nt
	global_store_dwordx2 v2, v[210:211], s[16:17] offset:1024 nt
	global_store_dwordx2 v2, v[212:213], s[16:17] offset:1536 nt
	global_store_dword v3, v214, s[18:19] nt
	global_store_dword v3, v215, s[18:19] offset:256 nt
	global_store_dword v3, v216, s[18:19] offset:512 nt
	global_store_dword v3, v217, s[18:19] offset:768 nt
	s_add_u32 s16, s16, 0x400000
	s_addc_u32 s17, s17, 0
	s_add_u32 s18, s18, 0x200000
	s_addc_u32 s19, s19, 0
	global_load_dwordx4 v[188:191], v1, s[20:21] nt
	global_load_dwordx4 v[192:195], v1, s[20:21] offset:1024 nt
	global_load_dwordx4 v[196:199], v1, s[20:21] offset:2048 nt
	global_load_dwordx4 v[200:203], v1, s[20:21] offset:3072 nt
	s_add_u32 s20, s20, 0x800000
	s_addc_u32 s21, s21, 0
	s_waitcnt vmcnt(44)
	v_pk_mul_f32 v[54:55], v[4:5], v[4:5]
	v_pk_mul_f32 v[56:57], v[6:7], v[6:7]
	v_pk_fma_f32 v[54:55], v[8:9], v[8:9], v[54:55]
	v_pk_fma_f32 v[56:57], v[10:11], v[10:11], v[56:57]
	v_pk_fma_f32 v[54:55], v[12:13], v[12:13], v[54:55]
	v_pk_fma_f32 v[56:57], v[14:15], v[14:15], v[56:57]
	v_pk_fma_f32 v[54:55], v[16:17], v[16:17], v[54:55]
	v_pk_fma_f32 v[56:57], v[18:19], v[18:19], v[56:57]
	v_pk_add_f32 v[54:55], v[54:55], v[56:57]
	s_nop 0
	v_add_f32_e32 v52, v54, v55
	s_nop 1
	v_add_f32_dpp v52, v52, v52 quad_perm:[1,0,3,2] row_mask:0xf bank_mask:0xf
	s_nop 1
	v_add_f32_dpp v52, v52, v52 quad_perm:[2,3,0,1] row_mask:0xf bank_mask:0xf
	s_nop 1
	v_add_f32_dpp v52, v52, v52 row_half_mirror row_mask:0xf bank_mask:0xf
	s_nop 1
	v_add_f32_dpp v52, v52, v52 row_mirror row_mask:0xf bank_mask:0xf
	s_nop 1
	v_add_f32_dpp v52, v52, v52 row_bcast:15 row_mask:0xa bank_mask:0xf
	s_nop 1
	v_add_f32_dpp v52, v52, v52 row_bcast:31 row_mask:0xc bank_mask:0xf
	s_nop 1
	v_readlane_b32 s27, v52, 63
	s_nop 3
	v_mov_b32_e32 v52, s27
	v_fmamk_f32 v52, v52, 0x3a800000, v204
	v_rsq_f32_e32 v52, v52
	s_nop 1
	v_pk_mul_f32 v[4:5], v[4:5], v[52:53] op_sel_hi:[1,0]
	v_pk_mul_f32 v[6:7], v[6:7], v[52:53] op_sel_hi:[1,0]
	v_pk_mul_f32 v[8:9], v[8:9], v[52:53] op_sel_hi:[1,0]
	v_pk_mul_f32 v[10:11], v[10:11], v[52:53] op_sel_hi:[1,0]
	v_pk_mul_f32 v[12:13], v[12:13], v[52:53] op_sel_hi:[1,0]
	v_pk_mul_f32 v[14:15], v[14:15], v[52:53] op_sel_hi:[1,0]
	v_pk_mul_f32 v[16:17], v[16:17], v[52:53] op_sel_hi:[1,0]
	v_pk_mul_f32 v[18:19], v[18:19], v[52:53] op_sel_hi:[1,0]
	v_pk_mul_f32 v[4:5], v[172:173], v[4:5]
	v_pk_mul_f32 v[6:7], v[174:175], v[6:7]
	v_pk_mul_f32 v[8:9], v[176:177], v[8:9]
	v_pk_mul_f32 v[10:11], v[178:179], v[10:11]
	v_pk_mul_f32 v[12:13], v[180:181], v[12:13]
	v_pk_mul_f32 v[14:15], v[182:183], v[14:15]
	v_pk_mul_f32 v[16:17], v[184:185], v[16:17]
	v_pk_mul_f32 v[18:19], v[186:187], v[18:19]
	v_pk_add_f32 v[56:57], v[58:59], 1.0 op_sel_hi:[1,0]
	v_pk_fma_f32 v[4:5], v[56:57], v[4:5], v[74:75]
	v_pk_add_f32 v[56:57], v[60:61], 1.0 op_sel_hi:[1,0]
	v_pk_fma_f32 v[6:7], v[56:57], v[6:7], v[76:77]
	v_pk_add_f32 v[56:57], v[62:63], 1.0 op_sel_hi:[1,0]
	v_pk_fma_f32 v[8:9], v[56:57], v[8:9], v[78:79]
	v_pk_add_f32 v[56:57], v[64:65], 1.0 op_sel_hi:[1,0]
	v_pk_fma_f32 v[10:11], v[56:57], v[10:11], v[80:81]
	v_pk_add_f32 v[56:57], v[66:67], 1.0 op_sel_hi:[1,0]
	v_pk_fma_f32 v[12:13], v[56:57], v[12:13], v[82:83]
	v_pk_add_f32 v[56:57], v[68:69], 1.0 op_sel_hi:[1,0]
	v_pk_fma_f32 v[14:15], v[56:57], v[14:15], v[84:85]
	v_pk_add_f32 v[56:57], v[70:71], 1.0 op_sel_hi:[1,0]
	v_pk_fma_f32 v[16:17], v[56:57], v[16:17], v[86:87]
	v_pk_add_f32 v[56:57], v[72:73], 1.0 op_sel_hi:[1,0]
	v_pk_fma_f32 v[18:19], v[56:57], v[18:19], v[88:89]
	v_cvt_pk_bf16_f32 v206, v4, v5
	v_cvt_pk_bf16_f32 v207, v6, v7
	v_cvt_pk_fp8_f32 v214, v4, v5
	v_cvt_pk_bf16_f32 v208, v8, v9
	v_cvt_pk_bf16_f32 v209, v10, v11
	v_cvt_pk_fp8_f32 v215, v8, v9
	v_cvt_pk_bf16_f32 v210, v12, v13
	v_cvt_pk_bf16_f32 v211, v14, v15
	v_cvt_pk_fp8_f32 v216, v12, v13
	v_cvt_pk_bf16_f32 v212, v16, v17
	v_cvt_pk_bf16_f32 v213, v18, v19
	v_cvt_pk_fp8_f32 v217, v16, v17
	v_cvt_pk_fp8_f32 v214, v6, v7 op_sel:[0,0,1]
	v_cvt_pk_fp8_f32 v215, v10, v11 op_sel:[0,0,1]
	v_cvt_pk_fp8_f32 v216, v14, v15 op_sel:[0,0,1]
	v_cvt_pk_fp8_f32 v217, v18, v19 op_sel:[0,0,1]
	s_nop 1
	global_store_dwordx2 v2, v[206:207], s[16:17] nt
	global_store_dwordx2 v2, v[208:209], s[16:17] offset:512 nt
	global_store_dwordx2 v2, v[210:211], s[16:17] offset:1024 nt
	global_store_dwordx2 v2, v[212:213], s[16:17] offset:1536 nt
	global_store_dword v3, v214, s[18:19] nt
	global_store_dword v3, v215, s[18:19] offset:256 nt
	global_store_dword v3, v216, s[18:19] offset:512 nt
	global_store_dword v3, v217, s[18:19] offset:768 nt
	s_add_u32 s16, s16, 0x400000
	s_addc_u32 s17, s17, 0
	s_add_u32 s18, s18, 0x200000
	s_addc_u32 s19, s19, 0
	global_load_dwordx4 v[4:7], v1, s[20:21] nt
	global_load_dwordx4 v[8:11], v1, s[20:21] offset:1024 nt
	global_load_dwordx4 v[12:15], v1, s[20:21] offset:2048 nt
	global_load_dwordx4 v[16:19], v1, s[20:21] offset:3072 nt
	s_add_u32 s20, s20, 0x800000
	s_addc_u32 s21, s21, 0
	s_waitcnt vmcnt(44)
	v_pk_mul_f32 v[54:55], v[20:21], v[20:21]
	v_pk_mul_f32 v[56:57], v[22:23], v[22:23]
	v_pk_fma_f32 v[54:55], v[24:25], v[24:25], v[54:55]
	v_pk_fma_f32 v[56:57], v[26:27], v[26:27], v[56:57]
	v_pk_fma_f32 v[54:55], v[28:29], v[28:29], v[54:55]
	v_pk_fma_f32 v[56:57], v[30:31], v[30:31], v[56:57]
	v_pk_fma_f32 v[54:55], v[32:33], v[32:33], v[54:55]
	v_pk_fma_f32 v[56:57], v[34:35], v[34:35], v[56:57]
	v_pk_add_f32 v[54:55], v[54:55], v[56:57]
	s_nop 0
	v_add_f32_e32 v52, v54, v55
	s_nop 1
	v_add_f32_dpp v52, v52, v52 quad_perm:[1,0,3,2] row_mask:0xf bank_mask:0xf
	s_nop 1
	v_add_f32_dpp v52, v52, v52 quad_perm:[2,3,0,1] row_mask:0xf bank_mask:0xf
	s_nop 1
	v_add_f32_dpp v52, v52, v52 row_half_mirror row_mask:0xf bank_mask:0xf
	s_nop 1
	v_add_f32_dpp v52, v52, v52 row_mirror row_mask:0xf bank_mask:0xf
	s_nop 1
	v_add_f32_dpp v52, v52, v52 row_bcast:15 row_mask:0xa bank_mask:0xf
	s_nop 1
	v_add_f32_dpp v52, v52, v52 row_bcast:31 row_mask:0xc bank_mask:0xf
	s_nop 1
	v_readlane_b32 s27, v52, 63
	s_nop 3
	v_mov_b32_e32 v52, s27
	v_fmamk_f32 v52, v52, 0x3a800000, v204
	v_rsq_f32_e32 v52, v52
	s_nop 1
	v_pk_mul_f32 v[20:21], v[20:21], v[52:53] op_sel_hi:[1,0]
	v_pk_mul_f32 v[22:23], v[22:23], v[52:53] op_sel_hi:[1,0]
	v_pk_mul_f32 v[24:25], v[24:25], v[52:53] op_sel_hi:[1,0]
	v_pk_mul_f32 v[26:27], v[26:27], v[52:53] op_sel_hi:[1,0]
	v_pk_mul_f32 v[28:29], v[28:29], v[52:53] op_sel_hi:[1,0]
	v_pk_mul_f32 v[30:31], v[30:31], v[52:53] op_sel_hi:[1,0]
	v_pk_mul_f32 v[32:33], v[32:33], v[52:53] op_sel_hi:[1,0]
	v_pk_mul_f32 v[34:35], v[34:35], v[52:53] op_sel_hi:[1,0]
	v_pk_mul_f32 v[20:21], v[172:173], v[20:21]
	v_pk_mul_f32 v[22:23], v[174:175], v[22:23]
	v_pk_mul_f32 v[24:25], v[176:177], v[24:25]
	v_pk_mul_f32 v[26:27], v[178:179], v[26:27]
	v_pk_mul_f32 v[28:29], v[180:181], v[28:29]
	v_pk_mul_f32 v[30:31], v[182:183], v[30:31]
	v_pk_mul_f32 v[32:33], v[184:185], v[32:33]
	v_pk_mul_f32 v[34:35], v[186:187], v[34:35]
	v_pk_add_f32 v[56:57], v[58:59], 1.0 op_sel_hi:[1,0]
	v_pk_fma_f32 v[20:21], v[56:57], v[20:21], v[74:75]
	v_pk_add_f32 v[56:57], v[60:61], 1.0 op_sel_hi:[1,0]
	v_pk_fma_f32 v[22:23], v[56:57], v[22:23], v[76:77]
	v_pk_add_f32 v[56:57], v[62:63], 1.0 op_sel_hi:[1,0]
	v_pk_fma_f32 v[24:25], v[56:57], v[24:25], v[78:79]
	v_pk_add_f32 v[56:57], v[64:65], 1.0 op_sel_hi:[1,0]
	v_pk_fma_f32 v[26:27], v[56:57], v[26:27], v[80:81]
	v_pk_add_f32 v[56:57], v[66:67], 1.0 op_sel_hi:[1,0]
	v_pk_fma_f32 v[28:29], v[56:57], v[28:29], v[82:83]
	v_pk_add_f32 v[56:57], v[68:69], 1.0 op_sel_hi:[1,0]
	v_pk_fma_f32 v[30:31], v[56:57], v[30:31], v[84:85]
	v_pk_add_f32 v[56:57], v[70:71], 1.0 op_sel_hi:[1,0]
	v_pk_fma_f32 v[32:33], v[56:57], v[32:33], v[86:87]
	v_pk_add_f32 v[56:57], v[72:73], 1.0 op_sel_hi:[1,0]
	v_pk_fma_f32 v[34:35], v[56:57], v[34:35], v[88:89]
	v_cvt_pk_bf16_f32 v206, v20, v21
	v_cvt_pk_bf16_f32 v207, v22, v23
	v_cvt_pk_fp8_f32 v214, v20, v21
	v_cvt_pk_bf16_f32 v208, v24, v25
	v_cvt_pk_bf16_f32 v209, v26, v27
	v_cvt_pk_fp8_f32 v215, v24, v25
	v_cvt_pk_bf16_f32 v210, v28, v29
	v_cvt_pk_bf16_f32 v211, v30, v31
	v_cvt_pk_fp8_f32 v216, v28, v29
	v_cvt_pk_bf16_f32 v212, v32, v33
	v_cvt_pk_bf16_f32 v213, v34, v35
	v_cvt_pk_fp8_f32 v217, v32, v33
	v_cvt_pk_fp8_f32 v214, v22, v23 op_sel:[0,0,1]
	v_cvt_pk_fp8_f32 v215, v26, v27 op_sel:[0,0,1]
	v_cvt_pk_fp8_f32 v216, v30, v31 op_sel:[0,0,1]
	v_cvt_pk_fp8_f32 v217, v34, v35 op_sel:[0,0,1]
	s_nop 1
	global_store_dwordx2 v2, v[206:207], s[16:17] nt
	global_store_dwordx2 v2, v[208:209], s[16:17] offset:512 nt
	global_store_dwordx2 v2, v[210:211], s[16:17] offset:1024 nt
	global_store_dwordx2 v2, v[212:213], s[16:17] offset:1536 nt
	global_store_dword v3, v214, s[18:19] nt
	global_store_dword v3, v215, s[18:19] offset:256 nt
	global_store_dword v3, v216, s[18:19] offset:512 nt
	global_store_dword v3, v217, s[18:19] offset:768 nt
	s_add_u32 s16, s16, 0x400000
	s_addc_u32 s17, s17, 0
	s_add_u32 s18, s18, 0x200000
	s_addc_u32 s19, s19, 0
	global_load_dwordx4 v[20:23], v1, s[20:21] nt
	global_load_dwordx4 v[24:27], v1, s[20:21] offset:1024 nt
	global_load_dwordx4 v[28:31], v1, s[20:21] offset:2048 nt
	global_load_dwordx4 v[32:35], v1, s[20:21] offset:3072 nt
	s_add_u32 s20, s20, 0x800000
	s_addc_u32 s21, s21, 0
	s_waitcnt vmcnt(44)
	v_pk_mul_f32 v[54:55], v[36:37], v[36:37]
	v_pk_mul_f32 v[56:57], v[38:39], v[38:39]
	v_pk_fma_f32 v[54:55], v[40:41], v[40:41], v[54:55]
	v_pk_fma_f32 v[56:57], v[42:43], v[42:43], v[56:57]
	v_pk_fma_f32 v[54:55], v[44:45], v[44:45], v[54:55]
	v_pk_fma_f32 v[56:57], v[46:47], v[46:47], v[56:57]
	v_pk_fma_f32 v[54:55], v[48:49], v[48:49], v[54:55]
	v_pk_fma_f32 v[56:57], v[50:51], v[50:51], v[56:57]
	v_pk_add_f32 v[54:55], v[54:55], v[56:57]
	s_nop 0
	v_add_f32_e32 v52, v54, v55
	s_nop 1
	v_add_f32_dpp v52, v52, v52 quad_perm:[1,0,3,2] row_mask:0xf bank_mask:0xf
	s_nop 1
	v_add_f32_dpp v52, v52, v52 quad_perm:[2,3,0,1] row_mask:0xf bank_mask:0xf
	s_nop 1
	v_add_f32_dpp v52, v52, v52 row_half_mirror row_mask:0xf bank_mask:0xf
	s_nop 1
	v_add_f32_dpp v52, v52, v52 row_mirror row_mask:0xf bank_mask:0xf
	s_nop 1
	v_add_f32_dpp v52, v52, v52 row_bcast:15 row_mask:0xa bank_mask:0xf
	s_nop 1
	v_add_f32_dpp v52, v52, v52 row_bcast:31 row_mask:0xc bank_mask:0xf
	s_nop 1
	v_readlane_b32 s27, v52, 63
	s_nop 3
	v_mov_b32_e32 v52, s27
	v_fmamk_f32 v52, v52, 0x3a800000, v204
	v_rsq_f32_e32 v52, v52
	s_nop 1
	v_pk_mul_f32 v[36:37], v[36:37], v[52:53] op_sel_hi:[1,0]
	v_pk_mul_f32 v[38:39], v[38:39], v[52:53] op_sel_hi:[1,0]
	v_pk_mul_f32 v[40:41], v[40:41], v[52:53] op_sel_hi:[1,0]
	v_pk_mul_f32 v[42:43], v[42:43], v[52:53] op_sel_hi:[1,0]
	v_pk_mul_f32 v[44:45], v[44:45], v[52:53] op_sel_hi:[1,0]
	v_pk_mul_f32 v[46:47], v[46:47], v[52:53] op_sel_hi:[1,0]
	v_pk_mul_f32 v[48:49], v[48:49], v[52:53] op_sel_hi:[1,0]
	v_pk_mul_f32 v[50:51], v[50:51], v[52:53] op_sel_hi:[1,0]
	v_pk_mul_f32 v[36:37], v[172:173], v[36:37]
	v_pk_mul_f32 v[38:39], v[174:175], v[38:39]
	v_pk_mul_f32 v[40:41], v[176:177], v[40:41]
	v_pk_mul_f32 v[42:43], v[178:179], v[42:43]
	v_pk_mul_f32 v[44:45], v[180:181], v[44:45]
	v_pk_mul_f32 v[46:47], v[182:183], v[46:47]
	v_pk_mul_f32 v[48:49], v[184:185], v[48:49]
	v_pk_mul_f32 v[50:51], v[186:187], v[50:51]
	v_pk_add_f32 v[56:57], v[58:59], 1.0 op_sel_hi:[1,0]
	v_pk_fma_f32 v[36:37], v[56:57], v[36:37], v[74:75]
	v_pk_add_f32 v[56:57], v[60:61], 1.0 op_sel_hi:[1,0]
	v_pk_fma_f32 v[38:39], v[56:57], v[38:39], v[76:77]
	v_pk_add_f32 v[56:57], v[62:63], 1.0 op_sel_hi:[1,0]
	v_pk_fma_f32 v[40:41], v[56:57], v[40:41], v[78:79]
	v_pk_add_f32 v[56:57], v[64:65], 1.0 op_sel_hi:[1,0]
	v_pk_fma_f32 v[42:43], v[56:57], v[42:43], v[80:81]
	v_pk_add_f32 v[56:57], v[66:67], 1.0 op_sel_hi:[1,0]
	v_pk_fma_f32 v[44:45], v[56:57], v[44:45], v[82:83]
	v_pk_add_f32 v[56:57], v[68:69], 1.0 op_sel_hi:[1,0]
	v_pk_fma_f32 v[46:47], v[56:57], v[46:47], v[84:85]
	v_pk_add_f32 v[56:57], v[70:71], 1.0 op_sel_hi:[1,0]
	v_pk_fma_f32 v[48:49], v[56:57], v[48:49], v[86:87]
	v_pk_add_f32 v[56:57], v[72:73], 1.0 op_sel_hi:[1,0]
	v_pk_fma_f32 v[50:51], v[56:57], v[50:51], v[88:89]
	v_cvt_pk_bf16_f32 v206, v36, v37
	v_cvt_pk_bf16_f32 v207, v38, v39
	v_cvt_pk_fp8_f32 v214, v36, v37
	v_cvt_pk_bf16_f32 v208, v40, v41
	v_cvt_pk_bf16_f32 v209, v42, v43
	v_cvt_pk_fp8_f32 v215, v40, v41
	v_cvt_pk_bf16_f32 v210, v44, v45
	v_cvt_pk_bf16_f32 v211, v46, v47
	v_cvt_pk_fp8_f32 v216, v44, v45
	v_cvt_pk_bf16_f32 v212, v48, v49
	v_cvt_pk_bf16_f32 v213, v50, v51
	v_cvt_pk_fp8_f32 v217, v48, v49
	v_cvt_pk_fp8_f32 v214, v38, v39 op_sel:[0,0,1]
	v_cvt_pk_fp8_f32 v215, v42, v43 op_sel:[0,0,1]
	v_cvt_pk_fp8_f32 v216, v46, v47 op_sel:[0,0,1]
	v_cvt_pk_fp8_f32 v217, v50, v51 op_sel:[0,0,1]
	s_nop 1
	global_store_dwordx2 v2, v[206:207], s[16:17] nt
	global_store_dwordx2 v2, v[208:209], s[16:17] offset:512 nt
	global_store_dwordx2 v2, v[210:211], s[16:17] offset:1024 nt
	global_store_dwordx2 v2, v[212:213], s[16:17] offset:1536 nt
	global_store_dword v3, v214, s[18:19] nt
	global_store_dword v3, v215, s[18:19] offset:256 nt
	global_store_dword v3, v216, s[18:19] offset:512 nt
	global_store_dword v3, v217, s[18:19] offset:768 nt
	s_add_u32 s16, s16, 0x400000
	s_addc_u32 s17, s17, 0
	s_add_u32 s18, s18, 0x200000
	s_addc_u32 s19, s19, 0
	global_load_dwordx4 v[36:39], v1, s[20:21] nt
	global_load_dwordx4 v[40:43], v1, s[20:21] offset:1024 nt
	global_load_dwordx4 v[44:47], v1, s[20:21] offset:2048 nt
	global_load_dwordx4 v[48:51], v1, s[20:21] offset:3072 nt
	s_add_u32 s20, s20, 0x800000
	s_addc_u32 s21, s21, 0
	s_waitcnt vmcnt(36)
	v_pk_mul_f32 v[54:55], v[188:189], v[188:189]
	v_pk_mul_f32 v[56:57], v[190:191], v[190:191]
	v_pk_fma_f32 v[54:55], v[192:193], v[192:193], v[54:55]
	v_pk_fma_f32 v[56:57], v[194:195], v[194:195], v[56:57]
	v_pk_fma_f32 v[54:55], v[196:197], v[196:197], v[54:55]
	v_pk_fma_f32 v[56:57], v[198:199], v[198:199], v[56:57]
	v_pk_fma_f32 v[54:55], v[200:201], v[200:201], v[54:55]
	v_pk_fma_f32 v[56:57], v[202:203], v[202:203], v[56:57]
	v_pk_add_f32 v[54:55], v[54:55], v[56:57]
	s_nop 0
	v_add_f32_e32 v52, v54, v55
	s_nop 1
	v_add_f32_dpp v52, v52, v52 quad_perm:[1,0,3,2] row_mask:0xf bank_mask:0xf
	s_nop 1
	v_add_f32_dpp v52, v52, v52 quad_perm:[2,3,0,1] row_mask:0xf bank_mask:0xf
	s_nop 1
	v_add_f32_dpp v52, v52, v52 row_half_mirror row_mask:0xf bank_mask:0xf
	s_nop 1
	v_add_f32_dpp v52, v52, v52 row_mirror row_mask:0xf bank_mask:0xf
	s_nop 1
	v_add_f32_dpp v52, v52, v52 row_bcast:15 row_mask:0xa bank_mask:0xf
	s_nop 1
	v_add_f32_dpp v52, v52, v52 row_bcast:31 row_mask:0xc bank_mask:0xf
	s_nop 1
	v_readlane_b32 s27, v52, 63
	s_nop 3
	v_mov_b32_e32 v52, s27
	v_fmamk_f32 v52, v52, 0x3a800000, v204
	v_rsq_f32_e32 v52, v52
	s_nop 1
	v_pk_mul_f32 v[188:189], v[188:189], v[52:53] op_sel_hi:[1,0]
	v_pk_mul_f32 v[190:191], v[190:191], v[52:53] op_sel_hi:[1,0]
	v_pk_mul_f32 v[192:193], v[192:193], v[52:53] op_sel_hi:[1,0]
	v_pk_mul_f32 v[194:195], v[194:195], v[52:53] op_sel_hi:[1,0]
	v_pk_mul_f32 v[196:197], v[196:197], v[52:53] op_sel_hi:[1,0]
	v_pk_mul_f32 v[198:199], v[198:199], v[52:53] op_sel_hi:[1,0]
	v_pk_mul_f32 v[200:201], v[200:201], v[52:53] op_sel_hi:[1,0]
	v_pk_mul_f32 v[202:203], v[202:203], v[52:53] op_sel_hi:[1,0]
	v_pk_mul_f32 v[188:189], v[172:173], v[188:189]
	v_pk_mul_f32 v[190:191], v[174:175], v[190:191]
	v_pk_mul_f32 v[192:193], v[176:177], v[192:193]
	v_pk_mul_f32 v[194:195], v[178:179], v[194:195]
	v_pk_mul_f32 v[196:197], v[180:181], v[196:197]
	v_pk_mul_f32 v[198:199], v[182:183], v[198:199]
	v_pk_mul_f32 v[200:201], v[184:185], v[200:201]
	v_pk_mul_f32 v[202:203], v[186:187], v[202:203]
	v_pk_add_f32 v[56:57], v[58:59], 1.0 op_sel_hi:[1,0]
	v_pk_fma_f32 v[188:189], v[56:57], v[188:189], v[74:75]
	v_pk_add_f32 v[56:57], v[60:61], 1.0 op_sel_hi:[1,0]
	v_pk_fma_f32 v[190:191], v[56:57], v[190:191], v[76:77]
	v_pk_add_f32 v[56:57], v[62:63], 1.0 op_sel_hi:[1,0]
	v_pk_fma_f32 v[192:193], v[56:57], v[192:193], v[78:79]
	v_pk_add_f32 v[56:57], v[64:65], 1.0 op_sel_hi:[1,0]
	v_pk_fma_f32 v[194:195], v[56:57], v[194:195], v[80:81]
	v_pk_add_f32 v[56:57], v[66:67], 1.0 op_sel_hi:[1,0]
	v_pk_fma_f32 v[196:197], v[56:57], v[196:197], v[82:83]
	v_pk_add_f32 v[56:57], v[68:69], 1.0 op_sel_hi:[1,0]
	v_pk_fma_f32 v[198:199], v[56:57], v[198:199], v[84:85]
	v_pk_add_f32 v[56:57], v[70:71], 1.0 op_sel_hi:[1,0]
	v_pk_fma_f32 v[200:201], v[56:57], v[200:201], v[86:87]
	v_pk_add_f32 v[56:57], v[72:73], 1.0 op_sel_hi:[1,0]
	v_pk_fma_f32 v[202:203], v[56:57], v[202:203], v[88:89]
	s_add_u32 s22, s8, 0x12000
	s_addc_u32 s23, s9, 0
	s_add_u32 s24, s22, 0x1000
	s_addc_u32 s25, s23, 0
	global_load_dwordx4 v[58:61], v1, s[24:25]
	global_load_dwordx4 v[62:65], v1, s[24:25] offset:1024
	global_load_dwordx4 v[66:69], v1, s[24:25] offset:2048
	global_load_dwordx4 v[70:73], v1, s[24:25] offset:3072
	global_load_dwordx4 v[74:77], v1, s[22:23]
	global_load_dwordx4 v[78:81], v1, s[22:23] offset:1024
	global_load_dwordx4 v[82:85], v1, s[22:23] offset:2048
	global_load_dwordx4 v[86:89], v1, s[22:23] offset:3072
	v_cvt_pk_bf16_f32 v206, v188, v189
	v_cvt_pk_bf16_f32 v207, v190, v191
	v_cvt_pk_fp8_f32 v214, v188, v189
	v_cvt_pk_bf16_f32 v208, v192, v193
	v_cvt_pk_bf16_f32 v209, v194, v195
	v_cvt_pk_fp8_f32 v215, v192, v193
	v_cvt_pk_bf16_f32 v210, v196, v197
	v_cvt_pk_bf16_f32 v211, v198, v199
	v_cvt_pk_fp8_f32 v216, v196, v197
	v_cvt_pk_bf16_f32 v212, v200, v201
	v_cvt_pk_bf16_f32 v213, v202, v203
	v_cvt_pk_fp8_f32 v217, v200, v201
	v_cvt_pk_fp8_f32 v214, v190, v191 op_sel:[0,0,1]
	v_cvt_pk_fp8_f32 v215, v194, v195 op_sel:[0,0,1]
	v_cvt_pk_fp8_f32 v216, v198, v199 op_sel:[0,0,1]
	v_cvt_pk_fp8_f32 v217, v202, v203 op_sel:[0,0,1]
	s_nop 1
	global_store_dwordx2 v2, v[206:207], s[16:17] nt
	global_store_dwordx2 v2, v[208:209], s[16:17] offset:512 nt
	global_store_dwordx2 v2, v[210:211], s[16:17] offset:1024 nt
	global_store_dwordx2 v2, v[212:213], s[16:17] offset:1536 nt
	global_store_dword v3, v214, s[18:19] nt
	global_store_dword v3, v215, s[18:19] offset:256 nt
	global_store_dword v3, v216, s[18:19] offset:512 nt
	global_store_dword v3, v217, s[18:19] offset:768 nt
	s_add_u32 s16, s16, 0x400000
	s_addc_u32 s17, s17, 0
	s_add_u32 s18, s18, 0x200000
	s_addc_u32 s19, s19, 0
	global_load_dwordx4 v[188:191], v1, s[20:21] nt
	global_load_dwordx4 v[192:195], v1, s[20:21] offset:1024 nt
	global_load_dwordx4 v[196:199], v1, s[20:21] offset:2048 nt
	global_load_dwordx4 v[200:203], v1, s[20:21] offset:3072 nt
	s_add_u32 s20, s20, 0x800000
	s_addc_u32 s21, s21, 0
	s_waitcnt vmcnt(44)
	v_pk_mul_f32 v[54:55], v[4:5], v[4:5]
	v_pk_mul_f32 v[56:57], v[6:7], v[6:7]
	v_pk_fma_f32 v[54:55], v[8:9], v[8:9], v[54:55]
	v_pk_fma_f32 v[56:57], v[10:11], v[10:11], v[56:57]
	v_pk_fma_f32 v[54:55], v[12:13], v[12:13], v[54:55]
	v_pk_fma_f32 v[56:57], v[14:15], v[14:15], v[56:57]
	v_pk_fma_f32 v[54:55], v[16:17], v[16:17], v[54:55]
	v_pk_fma_f32 v[56:57], v[18:19], v[18:19], v[56:57]
	v_pk_add_f32 v[54:55], v[54:55], v[56:57]
	s_nop 0
	v_add_f32_e32 v52, v54, v55
	s_nop 1
	v_add_f32_dpp v52, v52, v52 quad_perm:[1,0,3,2] row_mask:0xf bank_mask:0xf
	s_nop 1
	v_add_f32_dpp v52, v52, v52 quad_perm:[2,3,0,1] row_mask:0xf bank_mask:0xf
	s_nop 1
	v_add_f32_dpp v52, v52, v52 row_half_mirror row_mask:0xf bank_mask:0xf
	s_nop 1
	v_add_f32_dpp v52, v52, v52 row_mirror row_mask:0xf bank_mask:0xf
	s_nop 1
	v_add_f32_dpp v52, v52, v52 row_bcast:15 row_mask:0xa bank_mask:0xf
	s_nop 1
	v_add_f32_dpp v52, v52, v52 row_bcast:31 row_mask:0xc bank_mask:0xf
	s_nop 1
	v_readlane_b32 s27, v52, 63
	s_nop 3
	v_mov_b32_e32 v52, s27
	v_fmamk_f32 v52, v52, 0x3a800000, v204
	v_rsq_f32_e32 v52, v52
	s_nop 1
	v_pk_mul_f32 v[4:5], v[4:5], v[52:53] op_sel_hi:[1,0]
	v_pk_mul_f32 v[6:7], v[6:7], v[52:53] op_sel_hi:[1,0]
	v_pk_mul_f32 v[8:9], v[8:9], v[52:53] op_sel_hi:[1,0]
	v_pk_mul_f32 v[10:11], v[10:11], v[52:53] op_sel_hi:[1,0]
	v_pk_mul_f32 v[12:13], v[12:13], v[52:53] op_sel_hi:[1,0]
	v_pk_mul_f32 v[14:15], v[14:15], v[52:53] op_sel_hi:[1,0]
	v_pk_mul_f32 v[16:17], v[16:17], v[52:53] op_sel_hi:[1,0]
	v_pk_mul_f32 v[18:19], v[18:19], v[52:53] op_sel_hi:[1,0]
	v_pk_mul_f32 v[4:5], v[172:173], v[4:5]
	v_pk_mul_f32 v[6:7], v[174:175], v[6:7]
	v_pk_mul_f32 v[8:9], v[176:177], v[8:9]
	v_pk_mul_f32 v[10:11], v[178:179], v[10:11]
	v_pk_mul_f32 v[12:13], v[180:181], v[12:13]
	v_pk_mul_f32 v[14:15], v[182:183], v[14:15]
	v_pk_mul_f32 v[16:17], v[184:185], v[16:17]
	v_pk_mul_f32 v[18:19], v[186:187], v[18:19]
	v_pk_add_f32 v[56:57], v[220:221], 1.0 op_sel_hi:[1,0]
	v_pk_fma_f32 v[4:5], v[56:57], v[4:5], v[236:237]
	v_pk_add_f32 v[56:57], v[222:223], 1.0 op_sel_hi:[1,0]
	v_pk_fma_f32 v[6:7], v[56:57], v[6:7], v[238:239]
	v_pk_add_f32 v[56:57], v[224:225], 1.0 op_sel_hi:[1,0]
	v_pk_fma_f32 v[8:9], v[56:57], v[8:9], v[240:241]
	v_pk_add_f32 v[56:57], v[226:227], 1.0 op_sel_hi:[1,0]
	v_pk_fma_f32 v[10:11], v[56:57], v[10:11], v[242:243]
	v_pk_add_f32 v[56:57], v[228:229], 1.0 op_sel_hi:[1,0]
	v_pk_fma_f32 v[12:13], v[56:57], v[12:13], v[244:245]
	v_pk_add_f32 v[56:57], v[230:231], 1.0 op_sel_hi:[1,0]
	v_pk_fma_f32 v[14:15], v[56:57], v[14:15], v[246:247]
	v_pk_add_f32 v[56:57], v[232:233], 1.0 op_sel_hi:[1,0]
	v_pk_fma_f32 v[16:17], v[56:57], v[16:17], v[248:249]
	v_pk_add_f32 v[56:57], v[234:235], 1.0 op_sel_hi:[1,0]
	v_pk_fma_f32 v[18:19], v[56:57], v[18:19], v[250:251]
	v_cvt_pk_bf16_f32 v206, v4, v5
	v_cvt_pk_bf16_f32 v207, v6, v7
	v_cvt_pk_fp8_f32 v214, v4, v5
	v_cvt_pk_bf16_f32 v208, v8, v9
	v_cvt_pk_bf16_f32 v209, v10, v11
	v_cvt_pk_fp8_f32 v215, v8, v9
	v_cvt_pk_bf16_f32 v210, v12, v13
	v_cvt_pk_bf16_f32 v211, v14, v15
	v_cvt_pk_fp8_f32 v216, v12, v13
	v_cvt_pk_bf16_f32 v212, v16, v17
	v_cvt_pk_bf16_f32 v213, v18, v19
	v_cvt_pk_fp8_f32 v217, v16, v17
	v_cvt_pk_fp8_f32 v214, v6, v7 op_sel:[0,0,1]
	v_cvt_pk_fp8_f32 v215, v10, v11 op_sel:[0,0,1]
	v_cvt_pk_fp8_f32 v216, v14, v15 op_sel:[0,0,1]
	v_cvt_pk_fp8_f32 v217, v18, v19 op_sel:[0,0,1]
	s_nop 1
	global_store_dwordx2 v2, v[206:207], s[16:17] nt
	global_store_dwordx2 v2, v[208:209], s[16:17] offset:512 nt
	global_store_dwordx2 v2, v[210:211], s[16:17] offset:1024 nt
	global_store_dwordx2 v2, v[212:213], s[16:17] offset:1536 nt
	global_store_dword v3, v214, s[18:19] nt
	global_store_dword v3, v215, s[18:19] offset:256 nt
	global_store_dword v3, v216, s[18:19] offset:512 nt
	global_store_dword v3, v217, s[18:19] offset:768 nt
	s_add_u32 s16, s16, 0x400000
	s_addc_u32 s17, s17, 0
	s_add_u32 s18, s18, 0x200000
	s_addc_u32 s19, s19, 0
	global_load_dwordx4 v[4:7], v1, s[20:21] nt
	global_load_dwordx4 v[8:11], v1, s[20:21] offset:1024 nt
	global_load_dwordx4 v[12:15], v1, s[20:21] offset:2048 nt
	global_load_dwordx4 v[16:19], v1, s[20:21] offset:3072 nt
	s_add_u32 s20, s20, 0x800000
	s_addc_u32 s21, s21, 0
	s_waitcnt vmcnt(44)
	v_pk_mul_f32 v[54:55], v[20:21], v[20:21]
	v_pk_mul_f32 v[56:57], v[22:23], v[22:23]
	v_pk_fma_f32 v[54:55], v[24:25], v[24:25], v[54:55]
	v_pk_fma_f32 v[56:57], v[26:27], v[26:27], v[56:57]
	v_pk_fma_f32 v[54:55], v[28:29], v[28:29], v[54:55]
	v_pk_fma_f32 v[56:57], v[30:31], v[30:31], v[56:57]
	v_pk_fma_f32 v[54:55], v[32:33], v[32:33], v[54:55]
	v_pk_fma_f32 v[56:57], v[34:35], v[34:35], v[56:57]
	v_pk_add_f32 v[54:55], v[54:55], v[56:57]
	s_nop 0
	v_add_f32_e32 v52, v54, v55
	s_nop 1
	v_add_f32_dpp v52, v52, v52 quad_perm:[1,0,3,2] row_mask:0xf bank_mask:0xf
	s_nop 1
	v_add_f32_dpp v52, v52, v52 quad_perm:[2,3,0,1] row_mask:0xf bank_mask:0xf
	s_nop 1
	v_add_f32_dpp v52, v52, v52 row_half_mirror row_mask:0xf bank_mask:0xf
	s_nop 1
	v_add_f32_dpp v52, v52, v52 row_mirror row_mask:0xf bank_mask:0xf
	s_nop 1
	v_add_f32_dpp v52, v52, v52 row_bcast:15 row_mask:0xa bank_mask:0xf
	s_nop 1
	v_add_f32_dpp v52, v52, v52 row_bcast:31 row_mask:0xc bank_mask:0xf
	s_nop 1
	v_readlane_b32 s27, v52, 63
	s_nop 3
	v_mov_b32_e32 v52, s27
	v_fmamk_f32 v52, v52, 0x3a800000, v204
	v_rsq_f32_e32 v52, v52
	s_nop 1
	v_pk_mul_f32 v[20:21], v[20:21], v[52:53] op_sel_hi:[1,0]
	v_pk_mul_f32 v[22:23], v[22:23], v[52:53] op_sel_hi:[1,0]
	v_pk_mul_f32 v[24:25], v[24:25], v[52:53] op_sel_hi:[1,0]
	v_pk_mul_f32 v[26:27], v[26:27], v[52:53] op_sel_hi:[1,0]
	v_pk_mul_f32 v[28:29], v[28:29], v[52:53] op_sel_hi:[1,0]
	v_pk_mul_f32 v[30:31], v[30:31], v[52:53] op_sel_hi:[1,0]
	v_pk_mul_f32 v[32:33], v[32:33], v[52:53] op_sel_hi:[1,0]
	v_pk_mul_f32 v[34:35], v[34:35], v[52:53] op_sel_hi:[1,0]
	v_pk_mul_f32 v[20:21], v[172:173], v[20:21]
	v_pk_mul_f32 v[22:23], v[174:175], v[22:23]
	v_pk_mul_f32 v[24:25], v[176:177], v[24:25]
	v_pk_mul_f32 v[26:27], v[178:179], v[26:27]
	v_pk_mul_f32 v[28:29], v[180:181], v[28:29]
	v_pk_mul_f32 v[30:31], v[182:183], v[30:31]
	v_pk_mul_f32 v[32:33], v[184:185], v[32:33]
	v_pk_mul_f32 v[34:35], v[186:187], v[34:35]
	v_pk_add_f32 v[56:57], v[220:221], 1.0 op_sel_hi:[1,0]
	v_pk_fma_f32 v[20:21], v[56:57], v[20:21], v[236:237]
	v_pk_add_f32 v[56:57], v[222:223], 1.0 op_sel_hi:[1,0]
	v_pk_fma_f32 v[22:23], v[56:57], v[22:23], v[238:239]
	v_pk_add_f32 v[56:57], v[224:225], 1.0 op_sel_hi:[1,0]
	v_pk_fma_f32 v[24:25], v[56:57], v[24:25], v[240:241]
	v_pk_add_f32 v[56:57], v[226:227], 1.0 op_sel_hi:[1,0]
	v_pk_fma_f32 v[26:27], v[56:57], v[26:27], v[242:243]
	v_pk_add_f32 v[56:57], v[228:229], 1.0 op_sel_hi:[1,0]
	v_pk_fma_f32 v[28:29], v[56:57], v[28:29], v[244:245]
	v_pk_add_f32 v[56:57], v[230:231], 1.0 op_sel_hi:[1,0]
	v_pk_fma_f32 v[30:31], v[56:57], v[30:31], v[246:247]
	v_pk_add_f32 v[56:57], v[232:233], 1.0 op_sel_hi:[1,0]
	v_pk_fma_f32 v[32:33], v[56:57], v[32:33], v[248:249]
	v_pk_add_f32 v[56:57], v[234:235], 1.0 op_sel_hi:[1,0]
	v_pk_fma_f32 v[34:35], v[56:57], v[34:35], v[250:251]
	v_cvt_pk_bf16_f32 v206, v20, v21
	v_cvt_pk_bf16_f32 v207, v22, v23
	v_cvt_pk_fp8_f32 v214, v20, v21
	v_cvt_pk_bf16_f32 v208, v24, v25
	v_cvt_pk_bf16_f32 v209, v26, v27
	v_cvt_pk_fp8_f32 v215, v24, v25
	v_cvt_pk_bf16_f32 v210, v28, v29
	v_cvt_pk_bf16_f32 v211, v30, v31
	v_cvt_pk_fp8_f32 v216, v28, v29
	v_cvt_pk_bf16_f32 v212, v32, v33
	v_cvt_pk_bf16_f32 v213, v34, v35
	v_cvt_pk_fp8_f32 v217, v32, v33
	v_cvt_pk_fp8_f32 v214, v22, v23 op_sel:[0,0,1]
	v_cvt_pk_fp8_f32 v215, v26, v27 op_sel:[0,0,1]
	v_cvt_pk_fp8_f32 v216, v30, v31 op_sel:[0,0,1]
	v_cvt_pk_fp8_f32 v217, v34, v35 op_sel:[0,0,1]
	s_nop 1
	global_store_dwordx2 v2, v[206:207], s[16:17] nt
	global_store_dwordx2 v2, v[208:209], s[16:17] offset:512 nt
	global_store_dwordx2 v2, v[210:211], s[16:17] offset:1024 nt
	global_store_dwordx2 v2, v[212:213], s[16:17] offset:1536 nt
	global_store_dword v3, v214, s[18:19] nt
	global_store_dword v3, v215, s[18:19] offset:256 nt
	global_store_dword v3, v216, s[18:19] offset:512 nt
	global_store_dword v3, v217, s[18:19] offset:768 nt
	s_add_u32 s16, s16, 0x400000
	s_addc_u32 s17, s17, 0
	s_add_u32 s18, s18, 0x200000
	s_addc_u32 s19, s19, 0
	global_load_dwordx4 v[20:23], v1, s[20:21] nt
	global_load_dwordx4 v[24:27], v1, s[20:21] offset:1024 nt
	global_load_dwordx4 v[28:31], v1, s[20:21] offset:2048 nt
	global_load_dwordx4 v[32:35], v1, s[20:21] offset:3072 nt
	s_add_u32 s20, s20, 0x800000
	s_addc_u32 s21, s21, 0
	s_waitcnt vmcnt(44)
	v_pk_mul_f32 v[54:55], v[36:37], v[36:37]
	v_pk_mul_f32 v[56:57], v[38:39], v[38:39]
	v_pk_fma_f32 v[54:55], v[40:41], v[40:41], v[54:55]
	v_pk_fma_f32 v[56:57], v[42:43], v[42:43], v[56:57]
	v_pk_fma_f32 v[54:55], v[44:45], v[44:45], v[54:55]
	v_pk_fma_f32 v[56:57], v[46:47], v[46:47], v[56:57]
	v_pk_fma_f32 v[54:55], v[48:49], v[48:49], v[54:55]
	v_pk_fma_f32 v[56:57], v[50:51], v[50:51], v[56:57]
	v_pk_add_f32 v[54:55], v[54:55], v[56:57]
	s_nop 0
	v_add_f32_e32 v52, v54, v55
	s_nop 1
	v_add_f32_dpp v52, v52, v52 quad_perm:[1,0,3,2] row_mask:0xf bank_mask:0xf
	s_nop 1
	v_add_f32_dpp v52, v52, v52 quad_perm:[2,3,0,1] row_mask:0xf bank_mask:0xf
	s_nop 1
	v_add_f32_dpp v52, v52, v52 row_half_mirror row_mask:0xf bank_mask:0xf
	s_nop 1
	v_add_f32_dpp v52, v52, v52 row_mirror row_mask:0xf bank_mask:0xf
	s_nop 1
	v_add_f32_dpp v52, v52, v52 row_bcast:15 row_mask:0xa bank_mask:0xf
	s_nop 1
	v_add_f32_dpp v52, v52, v52 row_bcast:31 row_mask:0xc bank_mask:0xf
	s_nop 1
	v_readlane_b32 s27, v52, 63
	s_nop 3
	v_mov_b32_e32 v52, s27
	v_fmamk_f32 v52, v52, 0x3a800000, v204
	v_rsq_f32_e32 v52, v52
	s_nop 1
	v_pk_mul_f32 v[36:37], v[36:37], v[52:53] op_sel_hi:[1,0]
	v_pk_mul_f32 v[38:39], v[38:39], v[52:53] op_sel_hi:[1,0]
	v_pk_mul_f32 v[40:41], v[40:41], v[52:53] op_sel_hi:[1,0]
	v_pk_mul_f32 v[42:43], v[42:43], v[52:53] op_sel_hi:[1,0]
	v_pk_mul_f32 v[44:45], v[44:45], v[52:53] op_sel_hi:[1,0]
	v_pk_mul_f32 v[46:47], v[46:47], v[52:53] op_sel_hi:[1,0]
	v_pk_mul_f32 v[48:49], v[48:49], v[52:53] op_sel_hi:[1,0]
	v_pk_mul_f32 v[50:51], v[50:51], v[52:53] op_sel_hi:[1,0]
	v_pk_mul_f32 v[36:37], v[172:173], v[36:37]
	v_pk_mul_f32 v[38:39], v[174:175], v[38:39]
	v_pk_mul_f32 v[40:41], v[176:177], v[40:41]
	v_pk_mul_f32 v[42:43], v[178:179], v[42:43]
	v_pk_mul_f32 v[44:45], v[180:181], v[44:45]
	v_pk_mul_f32 v[46:47], v[182:183], v[46:47]
	v_pk_mul_f32 v[48:49], v[184:185], v[48:49]
	v_pk_mul_f32 v[50:51], v[186:187], v[50:51]
	v_pk_add_f32 v[56:57], v[220:221], 1.0 op_sel_hi:[1,0]
	v_pk_fma_f32 v[36:37], v[56:57], v[36:37], v[236:237]
	v_pk_add_f32 v[56:57], v[222:223], 1.0 op_sel_hi:[1,0]
	v_pk_fma_f32 v[38:39], v[56:57], v[38:39], v[238:239]
	v_pk_add_f32 v[56:57], v[224:225], 1.0 op_sel_hi:[1,0]
	v_pk_fma_f32 v[40:41], v[56:57], v[40:41], v[240:241]
	v_pk_add_f32 v[56:57], v[226:227], 1.0 op_sel_hi:[1,0]
	v_pk_fma_f32 v[42:43], v[56:57], v[42:43], v[242:243]
	v_pk_add_f32 v[56:57], v[228:229], 1.0 op_sel_hi:[1,0]
	v_pk_fma_f32 v[44:45], v[56:57], v[44:45], v[244:245]
	v_pk_add_f32 v[56:57], v[230:231], 1.0 op_sel_hi:[1,0]
	v_pk_fma_f32 v[46:47], v[56:57], v[46:47], v[246:247]
	v_pk_add_f32 v[56:57], v[232:233], 1.0 op_sel_hi:[1,0]
	v_pk_fma_f32 v[48:49], v[56:57], v[48:49], v[248:249]
	v_pk_add_f32 v[56:57], v[234:235], 1.0 op_sel_hi:[1,0]
	v_pk_fma_f32 v[50:51], v[56:57], v[50:51], v[250:251]
	v_cvt_pk_bf16_f32 v206, v36, v37
	v_cvt_pk_bf16_f32 v207, v38, v39
	v_cvt_pk_fp8_f32 v214, v36, v37
	v_cvt_pk_bf16_f32 v208, v40, v41
	v_cvt_pk_bf16_f32 v209, v42, v43
	v_cvt_pk_fp8_f32 v215, v40, v41
	v_cvt_pk_bf16_f32 v210, v44, v45
	v_cvt_pk_bf16_f32 v211, v46, v47
	v_cvt_pk_fp8_f32 v216, v44, v45
	v_cvt_pk_bf16_f32 v212, v48, v49
	v_cvt_pk_bf16_f32 v213, v50, v51
	v_cvt_pk_fp8_f32 v217, v48, v49
	v_cvt_pk_fp8_f32 v214, v38, v39 op_sel:[0,0,1]
	v_cvt_pk_fp8_f32 v215, v42, v43 op_sel:[0,0,1]
	v_cvt_pk_fp8_f32 v216, v46, v47 op_sel:[0,0,1]
	v_cvt_pk_fp8_f32 v217, v50, v51 op_sel:[0,0,1]
	s_nop 1
	global_store_dwordx2 v2, v[206:207], s[16:17] nt
	global_store_dwordx2 v2, v[208:209], s[16:17] offset:512 nt
	global_store_dwordx2 v2, v[210:211], s[16:17] offset:1024 nt
	global_store_dwordx2 v2, v[212:213], s[16:17] offset:1536 nt
	global_store_dword v3, v214, s[18:19] nt
	global_store_dword v3, v215, s[18:19] offset:256 nt
	global_store_dword v3, v216, s[18:19] offset:512 nt
	global_store_dword v3, v217, s[18:19] offset:768 nt
	s_add_u32 s16, s16, 0x400000
	s_addc_u32 s17, s17, 0
	s_add_u32 s18, s18, 0x200000
	s_addc_u32 s19, s19, 0
	global_load_dwordx4 v[36:39], v1, s[20:21] nt
	global_load_dwordx4 v[40:43], v1, s[20:21] offset:1024 nt
	global_load_dwordx4 v[44:47], v1, s[20:21] offset:2048 nt
	global_load_dwordx4 v[48:51], v1, s[20:21] offset:3072 nt
	s_add_u32 s20, s20, 0x800000
	s_addc_u32 s21, s21, 0
	s_waitcnt vmcnt(36)
	v_pk_mul_f32 v[54:55], v[188:189], v[188:189]
	v_pk_mul_f32 v[56:57], v[190:191], v[190:191]
	v_pk_fma_f32 v[54:55], v[192:193], v[192:193], v[54:55]
	v_pk_fma_f32 v[56:57], v[194:195], v[194:195], v[56:57]
	v_pk_fma_f32 v[54:55], v[196:197], v[196:197], v[54:55]
	v_pk_fma_f32 v[56:57], v[198:199], v[198:199], v[56:57]
	v_pk_fma_f32 v[54:55], v[200:201], v[200:201], v[54:55]
	v_pk_fma_f32 v[56:57], v[202:203], v[202:203], v[56:57]
	v_pk_add_f32 v[54:55], v[54:55], v[56:57]
	s_nop 0
	v_add_f32_e32 v52, v54, v55
	s_nop 1
	v_add_f32_dpp v52, v52, v52 quad_perm:[1,0,3,2] row_mask:0xf bank_mask:0xf
	s_nop 1
	v_add_f32_dpp v52, v52, v52 quad_perm:[2,3,0,1] row_mask:0xf bank_mask:0xf
	s_nop 1
	v_add_f32_dpp v52, v52, v52 row_half_mirror row_mask:0xf bank_mask:0xf
	s_nop 1
	v_add_f32_dpp v52, v52, v52 row_mirror row_mask:0xf bank_mask:0xf
	s_nop 1
	v_add_f32_dpp v52, v52, v52 row_bcast:15 row_mask:0xa bank_mask:0xf
	s_nop 1
	v_add_f32_dpp v52, v52, v52 row_bcast:31 row_mask:0xc bank_mask:0xf
	s_nop 1
	v_readlane_b32 s27, v52, 63
	s_nop 3
	v_mov_b32_e32 v52, s27
	v_fmamk_f32 v52, v52, 0x3a800000, v204
	v_rsq_f32_e32 v52, v52
	s_nop 1
	v_pk_mul_f32 v[188:189], v[188:189], v[52:53] op_sel_hi:[1,0]
	v_pk_mul_f32 v[190:191], v[190:191], v[52:53] op_sel_hi:[1,0]
	v_pk_mul_f32 v[192:193], v[192:193], v[52:53] op_sel_hi:[1,0]
	v_pk_mul_f32 v[194:195], v[194:195], v[52:53] op_sel_hi:[1,0]
	v_pk_mul_f32 v[196:197], v[196:197], v[52:53] op_sel_hi:[1,0]
	v_pk_mul_f32 v[198:199], v[198:199], v[52:53] op_sel_hi:[1,0]
	v_pk_mul_f32 v[200:201], v[200:201], v[52:53] op_sel_hi:[1,0]
	v_pk_mul_f32 v[202:203], v[202:203], v[52:53] op_sel_hi:[1,0]
	v_pk_mul_f32 v[188:189], v[172:173], v[188:189]
	v_pk_mul_f32 v[190:191], v[174:175], v[190:191]
	v_pk_mul_f32 v[192:193], v[176:177], v[192:193]
	v_pk_mul_f32 v[194:195], v[178:179], v[194:195]
	v_pk_mul_f32 v[196:197], v[180:181], v[196:197]
	v_pk_mul_f32 v[198:199], v[182:183], v[198:199]
	v_pk_mul_f32 v[200:201], v[184:185], v[200:201]
	v_pk_mul_f32 v[202:203], v[186:187], v[202:203]
	v_pk_add_f32 v[56:57], v[220:221], 1.0 op_sel_hi:[1,0]
	v_pk_fma_f32 v[188:189], v[56:57], v[188:189], v[236:237]
	v_pk_add_f32 v[56:57], v[222:223], 1.0 op_sel_hi:[1,0]
	v_pk_fma_f32 v[190:191], v[56:57], v[190:191], v[238:239]
	v_pk_add_f32 v[56:57], v[224:225], 1.0 op_sel_hi:[1,0]
	v_pk_fma_f32 v[192:193], v[56:57], v[192:193], v[240:241]
	v_pk_add_f32 v[56:57], v[226:227], 1.0 op_sel_hi:[1,0]
	v_pk_fma_f32 v[194:195], v[56:57], v[194:195], v[242:243]
	v_pk_add_f32 v[56:57], v[228:229], 1.0 op_sel_hi:[1,0]
	v_pk_fma_f32 v[196:197], v[56:57], v[196:197], v[244:245]
	v_pk_add_f32 v[56:57], v[230:231], 1.0 op_sel_hi:[1,0]
	v_pk_fma_f32 v[198:199], v[56:57], v[198:199], v[246:247]
	v_pk_add_f32 v[56:57], v[232:233], 1.0 op_sel_hi:[1,0]
	v_pk_fma_f32 v[200:201], v[56:57], v[200:201], v[248:249]
	v_pk_add_f32 v[56:57], v[234:235], 1.0 op_sel_hi:[1,0]
	v_pk_fma_f32 v[202:203], v[56:57], v[202:203], v[250:251]
	s_add_u32 s22, s8, 0x18000
	s_addc_u32 s23, s9, 0
	s_add_u32 s24, s22, 0x1000
	s_addc_u32 s25, s23, 0
	global_load_dwordx4 v[220:223], v1, s[24:25]
	global_load_dwordx4 v[224:227], v1, s[24:25] offset:1024
	global_load_dwordx4 v[228:231], v1, s[24:25] offset:2048
	global_load_dwordx4 v[232:235], v1, s[24:25] offset:3072
	global_load_dwordx4 v[236:239], v1, s[22:23]
	global_load_dwordx4 v[240:243], v1, s[22:23] offset:1024
	global_load_dwordx4 v[244:247], v1, s[22:23] offset:2048
	global_load_dwordx4 v[248:251], v1, s[22:23] offset:3072
	v_cvt_pk_bf16_f32 v206, v188, v189
	v_cvt_pk_bf16_f32 v207, v190, v191
	v_cvt_pk_fp8_f32 v214, v188, v189
	v_cvt_pk_bf16_f32 v208, v192, v193
	v_cvt_pk_bf16_f32 v209, v194, v195
	v_cvt_pk_fp8_f32 v215, v192, v193
	v_cvt_pk_bf16_f32 v210, v196, v197
	v_cvt_pk_bf16_f32 v211, v198, v199
	v_cvt_pk_fp8_f32 v216, v196, v197
	v_cvt_pk_bf16_f32 v212, v200, v201
	v_cvt_pk_bf16_f32 v213, v202, v203
	v_cvt_pk_fp8_f32 v217, v200, v201
	v_cvt_pk_fp8_f32 v214, v190, v191 op_sel:[0,0,1]
	v_cvt_pk_fp8_f32 v215, v194, v195 op_sel:[0,0,1]
	v_cvt_pk_fp8_f32 v216, v198, v199 op_sel:[0,0,1]
	v_cvt_pk_fp8_f32 v217, v202, v203 op_sel:[0,0,1]
	s_nop 1
	global_store_dwordx2 v2, v[206:207], s[16:17] nt
	global_store_dwordx2 v2, v[208:209], s[16:17] offset:512 nt
	global_store_dwordx2 v2, v[210:211], s[16:17] offset:1024 nt
	global_store_dwordx2 v2, v[212:213], s[16:17] offset:1536 nt
	global_store_dword v3, v214, s[18:19] nt
	global_store_dword v3, v215, s[18:19] offset:256 nt
	global_store_dword v3, v216, s[18:19] offset:512 nt
	global_store_dword v3, v217, s[18:19] offset:768 nt
	s_add_u32 s16, s16, 0x400000
	s_addc_u32 s17, s17, 0
	s_add_u32 s18, s18, 0x200000
	s_addc_u32 s19, s19, 0
	global_load_dwordx4 v[188:191], v1, s[20:21] nt
	global_load_dwordx4 v[192:195], v1, s[20:21] offset:1024 nt
	global_load_dwordx4 v[196:199], v1, s[20:21] offset:2048 nt
	global_load_dwordx4 v[200:203], v1, s[20:21] offset:3072 nt
	s_add_u32 s20, s20, 0x800000
	s_addc_u32 s21, s21, 0
	s_waitcnt vmcnt(44)
	v_pk_mul_f32 v[54:55], v[4:5], v[4:5]
	v_pk_mul_f32 v[56:57], v[6:7], v[6:7]
	v_pk_fma_f32 v[54:55], v[8:9], v[8:9], v[54:55]
	v_pk_fma_f32 v[56:57], v[10:11], v[10:11], v[56:57]
	v_pk_fma_f32 v[54:55], v[12:13], v[12:13], v[54:55]
	v_pk_fma_f32 v[56:57], v[14:15], v[14:15], v[56:57]
	v_pk_fma_f32 v[54:55], v[16:17], v[16:17], v[54:55]
	v_pk_fma_f32 v[56:57], v[18:19], v[18:19], v[56:57]
	v_pk_add_f32 v[54:55], v[54:55], v[56:57]
	s_nop 0
	v_add_f32_e32 v52, v54, v55
	s_nop 1
	v_add_f32_dpp v52, v52, v52 quad_perm:[1,0,3,2] row_mask:0xf bank_mask:0xf
	s_nop 1
	v_add_f32_dpp v52, v52, v52 quad_perm:[2,3,0,1] row_mask:0xf bank_mask:0xf
	s_nop 1
	v_add_f32_dpp v52, v52, v52 row_half_mirror row_mask:0xf bank_mask:0xf
	s_nop 1
	v_add_f32_dpp v52, v52, v52 row_mirror row_mask:0xf bank_mask:0xf
	s_nop 1
	v_add_f32_dpp v52, v52, v52 row_bcast:15 row_mask:0xa bank_mask:0xf
	s_nop 1
	v_add_f32_dpp v52, v52, v52 row_bcast:31 row_mask:0xc bank_mask:0xf
	s_nop 1
	v_readlane_b32 s27, v52, 63
	s_nop 3
	v_mov_b32_e32 v52, s27
	v_fmamk_f32 v52, v52, 0x3a800000, v204
	v_rsq_f32_e32 v52, v52
	s_nop 1
	v_pk_mul_f32 v[4:5], v[4:5], v[52:53] op_sel_hi:[1,0]
	v_pk_mul_f32 v[6:7], v[6:7], v[52:53] op_sel_hi:[1,0]
	v_pk_mul_f32 v[8:9], v[8:9], v[52:53] op_sel_hi:[1,0]
	v_pk_mul_f32 v[10:11], v[10:11], v[52:53] op_sel_hi:[1,0]
	v_pk_mul_f32 v[12:13], v[12:13], v[52:53] op_sel_hi:[1,0]
	v_pk_mul_f32 v[14:15], v[14:15], v[52:53] op_sel_hi:[1,0]
	v_pk_mul_f32 v[16:17], v[16:17], v[52:53] op_sel_hi:[1,0]
	v_pk_mul_f32 v[18:19], v[18:19], v[52:53] op_sel_hi:[1,0]
	v_pk_mul_f32 v[4:5], v[172:173], v[4:5]
	v_pk_mul_f32 v[6:7], v[174:175], v[6:7]
	v_pk_mul_f32 v[8:9], v[176:177], v[8:9]
	v_pk_mul_f32 v[10:11], v[178:179], v[10:11]
	v_pk_mul_f32 v[12:13], v[180:181], v[12:13]
	v_pk_mul_f32 v[14:15], v[182:183], v[14:15]
	v_pk_mul_f32 v[16:17], v[184:185], v[16:17]
	v_pk_mul_f32 v[18:19], v[186:187], v[18:19]
	v_pk_add_f32 v[56:57], v[58:59], 1.0 op_sel_hi:[1,0]
	v_pk_fma_f32 v[4:5], v[56:57], v[4:5], v[74:75]
	v_pk_add_f32 v[56:57], v[60:61], 1.0 op_sel_hi:[1,0]
	v_pk_fma_f32 v[6:7], v[56:57], v[6:7], v[76:77]
	v_pk_add_f32 v[56:57], v[62:63], 1.0 op_sel_hi:[1,0]
	v_pk_fma_f32 v[8:9], v[56:57], v[8:9], v[78:79]
	v_pk_add_f32 v[56:57], v[64:65], 1.0 op_sel_hi:[1,0]
	v_pk_fma_f32 v[10:11], v[56:57], v[10:11], v[80:81]
	v_pk_add_f32 v[56:57], v[66:67], 1.0 op_sel_hi:[1,0]
	v_pk_fma_f32 v[12:13], v[56:57], v[12:13], v[82:83]
	v_pk_add_f32 v[56:57], v[68:69], 1.0 op_sel_hi:[1,0]
	v_pk_fma_f32 v[14:15], v[56:57], v[14:15], v[84:85]
	v_pk_add_f32 v[56:57], v[70:71], 1.0 op_sel_hi:[1,0]
	v_pk_fma_f32 v[16:17], v[56:57], v[16:17], v[86:87]
	v_pk_add_f32 v[56:57], v[72:73], 1.0 op_sel_hi:[1,0]
	v_pk_fma_f32 v[18:19], v[56:57], v[18:19], v[88:89]
	v_cvt_pk_bf16_f32 v206, v4, v5
	v_cvt_pk_bf16_f32 v207, v6, v7
	v_cvt_pk_fp8_f32 v214, v4, v5
	v_cvt_pk_bf16_f32 v208, v8, v9
	v_cvt_pk_bf16_f32 v209, v10, v11
	v_cvt_pk_fp8_f32 v215, v8, v9
	v_cvt_pk_bf16_f32 v210, v12, v13
	v_cvt_pk_bf16_f32 v211, v14, v15
	v_cvt_pk_fp8_f32 v216, v12, v13
	v_cvt_pk_bf16_f32 v212, v16, v17
	v_cvt_pk_bf16_f32 v213, v18, v19
	v_cvt_pk_fp8_f32 v217, v16, v17
	v_cvt_pk_fp8_f32 v214, v6, v7 op_sel:[0,0,1]
	v_cvt_pk_fp8_f32 v215, v10, v11 op_sel:[0,0,1]
	v_cvt_pk_fp8_f32 v216, v14, v15 op_sel:[0,0,1]
	v_cvt_pk_fp8_f32 v217, v18, v19 op_sel:[0,0,1]
	s_nop 1
	global_store_dwordx2 v2, v[206:207], s[16:17] nt
	global_store_dwordx2 v2, v[208:209], s[16:17] offset:512 nt
	global_store_dwordx2 v2, v[210:211], s[16:17] offset:1024 nt
	global_store_dwordx2 v2, v[212:213], s[16:17] offset:1536 nt
	global_store_dword v3, v214, s[18:19] nt
	global_store_dword v3, v215, s[18:19] offset:256 nt
	global_store_dword v3, v216, s[18:19] offset:512 nt
	global_store_dword v3, v217, s[18:19] offset:768 nt
	s_add_u32 s16, s16, 0x400000
	s_addc_u32 s17, s17, 0
	s_add_u32 s18, s18, 0x200000
	s_addc_u32 s19, s19, 0
	s_cmp_lt_u32 s4, 0x400
	s_cbranch_scc0 .Lp1_noctx12
	global_load_dwordx4 v[4:7], v1, s[30:31] nt
	global_load_dwordx4 v[8:11], v1, s[30:31] offset:1024 nt
	global_load_dwordx4 v[12:15], v1, s[30:31] offset:2048 nt
	global_load_dwordx4 v[16:19], v1, s[30:31] offset:3072 nt
.Lp1_noctx12:
	s_waitcnt vmcnt(40)
	v_pk_mul_f32 v[54:55], v[20:21], v[20:21]
	v_pk_mul_f32 v[56:57], v[22:23], v[22:23]
	v_pk_fma_f32 v[54:55], v[24:25], v[24:25], v[54:55]
	v_pk_fma_f32 v[56:57], v[26:27], v[26:27], v[56:57]
	v_pk_fma_f32 v[54:55], v[28:29], v[28:29], v[54:55]
	v_pk_fma_f32 v[56:57], v[30:31], v[30:31], v[56:57]
	v_pk_fma_f32 v[54:55], v[32:33], v[32:33], v[54:55]
	v_pk_fma_f32 v[56:57], v[34:35], v[34:35], v[56:57]
	v_pk_add_f32 v[54:55], v[54:55], v[56:57]
	s_nop 0
	v_add_f32_e32 v52, v54, v55
	s_nop 1
	v_add_f32_dpp v52, v52, v52 quad_perm:[1,0,3,2] row_mask:0xf bank_mask:0xf
	s_nop 1
	v_add_f32_dpp v52, v52, v52 quad_perm:[2,3,0,1] row_mask:0xf bank_mask:0xf
	s_nop 1
	v_add_f32_dpp v52, v52, v52 row_half_mirror row_mask:0xf bank_mask:0xf
	s_nop 1
	v_add_f32_dpp v52, v52, v52 row_mirror row_mask:0xf bank_mask:0xf
	s_nop 1
	v_add_f32_dpp v52, v52, v52 row_bcast:15 row_mask:0xa bank_mask:0xf
	s_nop 1
	v_add_f32_dpp v52, v52, v52 row_bcast:31 row_mask:0xc bank_mask:0xf
	s_nop 1
	v_readlane_b32 s27, v52, 63
	s_nop 3
	v_mov_b32_e32 v52, s27
	v_fmamk_f32 v52, v52, 0x3a800000, v204
	v_rsq_f32_e32 v52, v52
	s_nop 1
	v_pk_mul_f32 v[20:21], v[20:21], v[52:53] op_sel_hi:[1,0]
	v_pk_mul_f32 v[22:23], v[22:23], v[52:53] op_sel_hi:[1,0]
	v_pk_mul_f32 v[24:25], v[24:25], v[52:53] op_sel_hi:[1,0]
	v_pk_mul_f32 v[26:27], v[26:27], v[52:53] op_sel_hi:[1,0]
	v_pk_mul_f32 v[28:29], v[28:29], v[52:53] op_sel_hi:[1,0]
	v_pk_mul_f32 v[30:31], v[30:31], v[52:53] op_sel_hi:[1,0]
	v_pk_mul_f32 v[32:33], v[32:33], v[52:53] op_sel_hi:[1,0]
	v_pk_mul_f32 v[34:35], v[34:35], v[52:53] op_sel_hi:[1,0]
	v_pk_mul_f32 v[20:21], v[172:173], v[20:21]
	v_pk_mul_f32 v[22:23], v[174:175], v[22:23]
	v_pk_mul_f32 v[24:25], v[176:177], v[24:25]
	v_pk_mul_f32 v[26:27], v[178:179], v[26:27]
	v_pk_mul_f32 v[28:29], v[180:181], v[28:29]
	v_pk_mul_f32 v[30:31], v[182:183], v[30:31]
	v_pk_mul_f32 v[32:33], v[184:185], v[32:33]
	v_pk_mul_f32 v[34:35], v[186:187], v[34:35]
	v_pk_add_f32 v[56:57], v[58:59], 1.0 op_sel_hi:[1,0]
	v_pk_fma_f32 v[20:21], v[56:57], v[20:21], v[74:75]
	v_pk_add_f32 v[56:57], v[60:61], 1.0 op_sel_hi:[1,0]
	v_pk_fma_f32 v[22:23], v[56:57], v[22:23], v[76:77]
	v_pk_add_f32 v[56:57], v[62:63], 1.0 op_sel_hi:[1,0]
	v_pk_fma_f32 v[24:25], v[56:57], v[24:25], v[78:79]
	v_pk_add_f32 v[56:57], v[64:65], 1.0 op_sel_hi:[1,0]
	v_pk_fma_f32 v[26:27], v[56:57], v[26:27], v[80:81]
	v_pk_add_f32 v[56:57], v[66:67], 1.0 op_sel_hi:[1,0]
	v_pk_fma_f32 v[28:29], v[56:57], v[28:29], v[82:83]
	v_pk_add_f32 v[56:57], v[68:69], 1.0 op_sel_hi:[1,0]
	v_pk_fma_f32 v[30:31], v[56:57], v[30:31], v[84:85]
	v_pk_add_f32 v[56:57], v[70:71], 1.0 op_sel_hi:[1,0]
	v_pk_fma_f32 v[32:33], v[56:57], v[32:33], v[86:87]
	v_pk_add_f32 v[56:57], v[72:73], 1.0 op_sel_hi:[1,0]
	v_pk_fma_f32 v[34:35], v[56:57], v[34:35], v[88:89]
	v_cvt_pk_bf16_f32 v206, v20, v21
	v_cvt_pk_bf16_f32 v207, v22, v23
	v_cvt_pk_fp8_f32 v214, v20, v21
	v_cvt_pk_bf16_f32 v208, v24, v25
	v_cvt_pk_bf16_f32 v209, v26, v27
	v_cvt_pk_fp8_f32 v215, v24, v25
	v_cvt_pk_bf16_f32 v210, v28, v29
	v_cvt_pk_bf16_f32 v211, v30, v31
	v_cvt_pk_fp8_f32 v216, v28, v29
	v_cvt_pk_bf16_f32 v212, v32, v33
	v_cvt_pk_bf16_f32 v213, v34, v35
	v_cvt_pk_fp8_f32 v217, v32, v33
	v_cvt_pk_fp8_f32 v214, v22, v23 op_sel:[0,0,1]
	v_cvt_pk_fp8_f32 v215, v26, v27 op_sel:[0,0,1]
	v_cvt_pk_fp8_f32 v216, v30, v31 op_sel:[0,0,1]
	v_cvt_pk_fp8_f32 v217, v34, v35 op_sel:[0,0,1]
	s_nop 1
	global_store_dwordx2 v2, v[206:207], s[16:17] nt
	global_store_dwordx2 v2, v[208:209], s[16:17] offset:512 nt
	global_store_dwordx2 v2, v[210:211], s[16:17] offset:1024 nt
	global_store_dwordx2 v2, v[212:213], s[16:17] offset:1536 nt
	global_store_dword v3, v214, s[18:19] nt
	global_store_dword v3, v215, s[18:19] offset:256 nt
	global_store_dword v3, v216, s[18:19] offset:512 nt
	global_store_dword v3, v217, s[18:19] offset:768 nt
	s_add_u32 s16, s16, 0x400000
	s_addc_u32 s17, s17, 0
	s_add_u32 s18, s18, 0x200000
	s_addc_u32 s19, s19, 0
	s_waitcnt vmcnt(36)
	v_pk_mul_f32 v[54:55], v[36:37], v[36:37]
	v_pk_mul_f32 v[56:57], v[38:39], v[38:39]
	v_pk_fma_f32 v[54:55], v[40:41], v[40:41], v[54:55]
	v_pk_fma_f32 v[56:57], v[42:43], v[42:43], v[56:57]
	v_pk_fma_f32 v[54:55], v[44:45], v[44:45], v[54:55]
	v_pk_fma_f32 v[56:57], v[46:47], v[46:47], v[56:57]
	v_pk_fma_f32 v[54:55], v[48:49], v[48:49], v[54:55]
	v_pk_fma_f32 v[56:57], v[50:51], v[50:51], v[56:57]
	v_pk_add_f32 v[54:55], v[54:55], v[56:57]
	s_nop 0
	v_add_f32_e32 v52, v54, v55
	s_nop 1
	v_add_f32_dpp v52, v52, v52 quad_perm:[1,0,3,2] row_mask:0xf bank_mask:0xf
	s_nop 1
	v_add_f32_dpp v52, v52, v52 quad_perm:[2,3,0,1] row_mask:0xf bank_mask:0xf
	s_nop 1
	v_add_f32_dpp v52, v52, v52 row_half_mirror row_mask:0xf bank_mask:0xf
	s_nop 1
	v_add_f32_dpp v52, v52, v52 row_mirror row_mask:0xf bank_mask:0xf
	s_nop 1
	v_add_f32_dpp v52, v52, v52 row_bcast:15 row_mask:0xa bank_mask:0xf
	s_nop 1
	v_add_f32_dpp v52, v52, v52 row_bcast:31 row_mask:0xc bank_mask:0xf
	s_nop 1
	v_readlane_b32 s27, v52, 63
	s_nop 3
	v_mov_b32_e32 v52, s27
	v_fmamk_f32 v52, v52, 0x3a800000, v204
	v_rsq_f32_e32 v52, v52
	s_nop 1
	v_pk_mul_f32 v[36:37], v[36:37], v[52:53] op_sel_hi:[1,0]
	v_pk_mul_f32 v[38:39], v[38:39], v[52:53] op_sel_hi:[1,0]
	v_pk_mul_f32 v[40:41], v[40:41], v[52:53] op_sel_hi:[1,0]
	v_pk_mul_f32 v[42:43], v[42:43], v[52:53] op_sel_hi:[1,0]
	v_pk_mul_f32 v[44:45], v[44:45], v[52:53] op_sel_hi:[1,0]
	v_pk_mul_f32 v[46:47], v[46:47], v[52:53] op_sel_hi:[1,0]
	v_pk_mul_f32 v[48:49], v[48:49], v[52:53] op_sel_hi:[1,0]
	v_pk_mul_f32 v[50:51], v[50:51], v[52:53] op_sel_hi:[1,0]
	v_pk_mul_f32 v[36:37], v[172:173], v[36:37]
	v_pk_mul_f32 v[38:39], v[174:175], v[38:39]
	v_pk_mul_f32 v[40:41], v[176:177], v[40:41]
	v_pk_mul_f32 v[42:43], v[178:179], v[42:43]
	v_pk_mul_f32 v[44:45], v[180:181], v[44:45]
	v_pk_mul_f32 v[46:47], v[182:183], v[46:47]
	v_pk_mul_f32 v[48:49], v[184:185], v[48:49]
	v_pk_mul_f32 v[50:51], v[186:187], v[50:51]
	v_pk_add_f32 v[56:57], v[58:59], 1.0 op_sel_hi:[1,0]
	v_pk_fma_f32 v[36:37], v[56:57], v[36:37], v[74:75]
	v_pk_add_f32 v[56:57], v[60:61], 1.0 op_sel_hi:[1,0]
	v_pk_fma_f32 v[38:39], v[56:57], v[38:39], v[76:77]
	v_pk_add_f32 v[56:57], v[62:63], 1.0 op_sel_hi:[1,0]
	v_pk_fma_f32 v[40:41], v[56:57], v[40:41], v[78:79]
	v_pk_add_f32 v[56:57], v[64:65], 1.0 op_sel_hi:[1,0]
	v_pk_fma_f32 v[42:43], v[56:57], v[42:43], v[80:81]
	v_pk_add_f32 v[56:57], v[66:67], 1.0 op_sel_hi:[1,0]
	v_pk_fma_f32 v[44:45], v[56:57], v[44:45], v[82:83]
	v_pk_add_f32 v[56:57], v[68:69], 1.0 op_sel_hi:[1,0]
	v_pk_fma_f32 v[46:47], v[56:57], v[46:47], v[84:85]
	v_pk_add_f32 v[56:57], v[70:71], 1.0 op_sel_hi:[1,0]
	v_pk_fma_f32 v[48:49], v[56:57], v[48:49], v[86:87]
	v_pk_add_f32 v[56:57], v[72:73], 1.0 op_sel_hi:[1,0]
	v_pk_fma_f32 v[50:51], v[56:57], v[50:51], v[88:89]
	v_cvt_pk_bf16_f32 v206, v36, v37
	v_cvt_pk_bf16_f32 v207, v38, v39
	v_cvt_pk_fp8_f32 v214, v36, v37
	v_cvt_pk_bf16_f32 v208, v40, v41
	v_cvt_pk_bf16_f32 v209, v42, v43
	v_cvt_pk_fp8_f32 v215, v40, v41
	v_cvt_pk_bf16_f32 v210, v44, v45
	v_cvt_pk_bf16_f32 v211, v46, v47
	v_cvt_pk_fp8_f32 v216, v44, v45
	v_cvt_pk_bf16_f32 v212, v48, v49
	v_cvt_pk_bf16_f32 v213, v50, v51
	v_cvt_pk_fp8_f32 v217, v48, v49
	v_cvt_pk_fp8_f32 v214, v38, v39 op_sel:[0,0,1]
	v_cvt_pk_fp8_f32 v215, v42, v43 op_sel:[0,0,1]
	v_cvt_pk_fp8_f32 v216, v46, v47 op_sel:[0,0,1]
	v_cvt_pk_fp8_f32 v217, v50, v51 op_sel:[0,0,1]
	s_nop 1
	global_store_dwordx2 v2, v[206:207], s[16:17] nt
	global_store_dwordx2 v2, v[208:209], s[16:17] offset:512 nt
	global_store_dwordx2 v2, v[210:211], s[16:17] offset:1024 nt
	global_store_dwordx2 v2, v[212:213], s[16:17] offset:1536 nt
	global_store_dword v3, v214, s[18:19] nt
	global_store_dword v3, v215, s[18:19] offset:256 nt
	global_store_dword v3, v216, s[18:19] offset:512 nt
	global_store_dword v3, v217, s[18:19] offset:768 nt
	s_add_u32 s16, s16, 0x400000
	s_addc_u32 s17, s17, 0
	s_add_u32 s18, s18, 0x200000
	s_addc_u32 s19, s19, 0
	s_waitcnt vmcnt(24)
	v_pk_mul_f32 v[54:55], v[188:189], v[188:189]
	v_pk_mul_f32 v[56:57], v[190:191], v[190:191]
	v_pk_fma_f32 v[54:55], v[192:193], v[192:193], v[54:55]
	v_pk_fma_f32 v[56:57], v[194:195], v[194:195], v[56:57]
	v_pk_fma_f32 v[54:55], v[196:197], v[196:197], v[54:55]
	v_pk_fma_f32 v[56:57], v[198:199], v[198:199], v[56:57]
	v_pk_fma_f32 v[54:55], v[200:201], v[200:201], v[54:55]
	v_pk_fma_f32 v[56:57], v[202:203], v[202:203], v[56:57]
	v_pk_add_f32 v[54:55], v[54:55], v[56:57]
	s_nop 0
	v_add_f32_e32 v52, v54, v55
	s_nop 1
	v_add_f32_dpp v52, v52, v52 quad_perm:[1,0,3,2] row_mask:0xf bank_mask:0xf
	s_nop 1
	v_add_f32_dpp v52, v52, v52 quad_perm:[2,3,0,1] row_mask:0xf bank_mask:0xf
	s_nop 1
	v_add_f32_dpp v52, v52, v52 row_half_mirror row_mask:0xf bank_mask:0xf
	s_nop 1
	v_add_f32_dpp v52, v52, v52 row_mirror row_mask:0xf bank_mask:0xf
	s_nop 1
	v_add_f32_dpp v52, v52, v52 row_bcast:15 row_mask:0xa bank_mask:0xf
	s_nop 1
	v_add_f32_dpp v52, v52, v52 row_bcast:31 row_mask:0xc bank_mask:0xf
	s_nop 1
	v_readlane_b32 s27, v52, 63
	s_nop 3
	v_mov_b32_e32 v52, s27
	v_fmamk_f32 v52, v52, 0x3a800000, v204
	v_rsq_f32_e32 v52, v52
	s_nop 1
	v_pk_mul_f32 v[188:189], v[188:189], v[52:53] op_sel_hi:[1,0]
	v_pk_mul_f32 v[190:191], v[190:191], v[52:53] op_sel_hi:[1,0]
	v_pk_mul_f32 v[192:193], v[192:193], v[52:53] op_sel_hi:[1,0]
	v_pk_mul_f32 v[194:195], v[194:195], v[52:53] op_sel_hi:[1,0]
	v_pk_mul_f32 v[196:197], v[196:197], v[52:53] op_sel_hi:[1,0]
	v_pk_mul_f32 v[198:199], v[198:199], v[52:53] op_sel_hi:[1,0]
	v_pk_mul_f32 v[200:201], v[200:201], v[52:53] op_sel_hi:[1,0]
	v_pk_mul_f32 v[202:203], v[202:203], v[52:53] op_sel_hi:[1,0]
	v_pk_mul_f32 v[188:189], v[172:173], v[188:189]
	v_pk_mul_f32 v[190:191], v[174:175], v[190:191]
	v_pk_mul_f32 v[192:193], v[176:177], v[192:193]
	v_pk_mul_f32 v[194:195], v[178:179], v[194:195]
	v_pk_mul_f32 v[196:197], v[180:181], v[196:197]
	v_pk_mul_f32 v[198:199], v[182:183], v[198:199]
	v_pk_mul_f32 v[200:201], v[184:185], v[200:201]
	v_pk_mul_f32 v[202:203], v[186:187], v[202:203]
	v_pk_add_f32 v[56:57], v[58:59], 1.0 op_sel_hi:[1,0]
	v_pk_fma_f32 v[188:189], v[56:57], v[188:189], v[74:75]
	v_pk_add_f32 v[56:57], v[60:61], 1.0 op_sel_hi:[1,0]
	v_pk_fma_f32 v[190:191], v[56:57], v[190:191], v[76:77]
	v_pk_add_f32 v[56:57], v[62:63], 1.0 op_sel_hi:[1,0]
	v_pk_fma_f32 v[192:193], v[56:57], v[192:193], v[78:79]
	v_pk_add_f32 v[56:57], v[64:65], 1.0 op_sel_hi:[1,0]
	v_pk_fma_f32 v[194:195], v[56:57], v[194:195], v[80:81]
	v_pk_add_f32 v[56:57], v[66:67], 1.0 op_sel_hi:[1,0]
	v_pk_fma_f32 v[196:197], v[56:57], v[196:197], v[82:83]
	v_pk_add_f32 v[56:57], v[68:69], 1.0 op_sel_hi:[1,0]
	v_pk_fma_f32 v[198:199], v[56:57], v[198:199], v[84:85]
	v_pk_add_f32 v[56:57], v[70:71], 1.0 op_sel_hi:[1,0]
	v_pk_fma_f32 v[200:201], v[56:57], v[200:201], v[86:87]
	v_pk_add_f32 v[56:57], v[72:73], 1.0 op_sel_hi:[1,0]
	v_pk_fma_f32 v[202:203], v[56:57], v[202:203], v[88:89]
	v_cvt_pk_bf16_f32 v206, v188, v189
	v_cvt_pk_bf16_f32 v207, v190, v191
	v_cvt_pk_fp8_f32 v214, v188, v189
	v_cvt_pk_bf16_f32 v208, v192, v193
	v_cvt_pk_bf16_f32 v209, v194, v195
	v_cvt_pk_fp8_f32 v215, v192, v193
	v_cvt_pk_bf16_f32 v210, v196, v197
	v_cvt_pk_bf16_f32 v211, v198, v199
	v_cvt_pk_fp8_f32 v216, v196, v197
	v_cvt_pk_bf16_f32 v212, v200, v201
	v_cvt_pk_bf16_f32 v213, v202, v203
	v_cvt_pk_fp8_f32 v217, v200, v201
	v_cvt_pk_fp8_f32 v214, v190, v191 op_sel:[0,0,1]
	v_cvt_pk_fp8_f32 v215, v194, v195 op_sel:[0,0,1]
	v_cvt_pk_fp8_f32 v216, v198, v199 op_sel:[0,0,1]
	v_cvt_pk_fp8_f32 v217, v202, v203 op_sel:[0,0,1]
	s_nop 1
	global_store_dwordx2 v2, v[206:207], s[16:17] nt
	global_store_dwordx2 v2, v[208:209], s[16:17] offset:512 nt
	global_store_dwordx2 v2, v[210:211], s[16:17] offset:1024 nt
	global_store_dwordx2 v2, v[212:213], s[16:17] offset:1536 nt
	global_store_dword v3, v214, s[18:19] nt
	global_store_dword v3, v215, s[18:19] offset:256 nt
	global_store_dword v3, v216, s[18:19] offset:512 nt
	global_store_dword v3, v217, s[18:19] offset:768 nt
	s_add_u32 s16, s16, 0x400000
	s_addc_u32 s17, s17, 0
	s_add_u32 s18, s18, 0x200000
	s_addc_u32 s19, s19, 0
	s_cmp_lt_u32 s4, 0x400
	s_cbranch_scc0 .Lp1_done
	s_waitcnt vmcnt(24)
	v_pk_mul_f32 v[54:55], v[4:5], v[4:5]
	v_pk_mul_f32 v[56:57], v[6:7], v[6:7]
	v_pk_fma_f32 v[54:55], v[8:9], v[8:9], v[54:55]
	v_pk_fma_f32 v[56:57], v[10:11], v[10:11], v[56:57]
	v_pk_fma_f32 v[54:55], v[12:13], v[12:13], v[54:55]
	v_pk_fma_f32 v[56:57], v[14:15], v[14:15], v[56:57]
	v_pk_fma_f32 v[54:55], v[16:17], v[16:17], v[54:55]
	v_pk_fma_f32 v[56:57], v[18:19], v[18:19], v[56:57]
	v_pk_add_f32 v[54:55], v[54:55], v[56:57]
	s_nop 0
	v_add_f32_e32 v52, v54, v55
	s_nop 1
	v_add_f32_dpp v52, v52, v52 quad_perm:[1,0,3,2] row_mask:0xf bank_mask:0xf
	s_nop 1
	v_add_f32_dpp v52, v52, v52 quad_perm:[2,3,0,1] row_mask:0xf bank_mask:0xf
	s_nop 1
	v_add_f32_dpp v52, v52, v52 row_half_mirror row_mask:0xf bank_mask:0xf
	s_nop 1
	v_add_f32_dpp v52, v52, v52 row_mirror row_mask:0xf bank_mask:0xf
	s_nop 1
	v_add_f32_dpp v52, v52, v52 row_bcast:15 row_mask:0xa bank_mask:0xf
	s_nop 1
	v_add_f32_dpp v52, v52, v52 row_bcast:31 row_mask:0xc bank_mask:0xf
	s_nop 1
	v_readlane_b32 s27, v52, 63
	s_nop 3
	v_mov_b32_e32 v52, s27
	v_fmamk_f32 v52, v52, 0x3a800000, v204
	v_rsq_f32_e32 v52, v52
	s_nop 1
	v_pk_mul_f32 v[4:5], v[4:5], v[52:53] op_sel_hi:[1,0]
	v_pk_mul_f32 v[6:7], v[6:7], v[52:53] op_sel_hi:[1,0]
	v_pk_mul_f32 v[8:9], v[8:9], v[52:53] op_sel_hi:[1,0]
	v_pk_mul_f32 v[10:11], v[10:11], v[52:53] op_sel_hi:[1,0]
	v_pk_mul_f32 v[12:13], v[12:13], v[52:53] op_sel_hi:[1,0]
	v_pk_mul_f32 v[14:15], v[14:15], v[52:53] op_sel_hi:[1,0]
	v_pk_mul_f32 v[16:17], v[16:17], v[52:53] op_sel_hi:[1,0]
	v_pk_mul_f32 v[18:19], v[18:19], v[52:53] op_sel_hi:[1,0]
	v_pk_mul_f32 v[4:5], v[172:173], v[4:5]
	v_pk_mul_f32 v[6:7], v[174:175], v[6:7]
	v_pk_mul_f32 v[8:9], v[176:177], v[8:9]
	v_pk_mul_f32 v[10:11], v[178:179], v[10:11]
	v_pk_mul_f32 v[12:13], v[180:181], v[12:13]
	v_pk_mul_f32 v[14:15], v[182:183], v[14:15]
	v_pk_mul_f32 v[16:17], v[184:185], v[16:17]
	v_pk_mul_f32 v[18:19], v[186:187], v[18:19]
	v_pk_add_f32 v[56:57], v[220:221], 1.0 op_sel_hi:[1,0]
	v_pk_fma_f32 v[4:5], v[56:57], v[4:5], v[236:237]
	v_pk_add_f32 v[56:57], v[222:223], 1.0 op_sel_hi:[1,0]
	v_pk_fma_f32 v[6:7], v[56:57], v[6:7], v[238:239]
	v_pk_add_f32 v[56:57], v[224:225], 1.0 op_sel_hi:[1,0]
	v_pk_fma_f32 v[8:9], v[56:57], v[8:9], v[240:241]
	v_pk_add_f32 v[56:57], v[226:227], 1.0 op_sel_hi:[1,0]
	v_pk_fma_f32 v[10:11], v[56:57], v[10:11], v[242:243]
	v_pk_add_f32 v[56:57], v[228:229], 1.0 op_sel_hi:[1,0]
	v_pk_fma_f32 v[12:13], v[56:57], v[12:13], v[244:245]
	v_pk_add_f32 v[56:57], v[230:231], 1.0 op_sel_hi:[1,0]
	v_pk_fma_f32 v[14:15], v[56:57], v[14:15], v[246:247]
	v_pk_add_f32 v[56:57], v[232:233], 1.0 op_sel_hi:[1,0]
	v_pk_fma_f32 v[16:17], v[56:57], v[16:17], v[248:249]
	v_pk_add_f32 v[56:57], v[234:235], 1.0 op_sel_hi:[1,0]
	v_pk_fma_f32 v[18:19], v[56:57], v[18:19], v[250:251]
	v_cvt_pk_bf16_f32 v206, v4, v5
	v_cvt_pk_bf16_f32 v207, v6, v7
	v_cvt_pk_fp8_f32 v214, v4, v5
	v_cvt_pk_bf16_f32 v208, v8, v9
	v_cvt_pk_bf16_f32 v209, v10, v11
	v_cvt_pk_fp8_f32 v215, v8, v9
	v_cvt_pk_bf16_f32 v210, v12, v13
	v_cvt_pk_bf16_f32 v211, v14, v15
	v_cvt_pk_fp8_f32 v216, v12, v13
	v_cvt_pk_bf16_f32 v212, v16, v17
	v_cvt_pk_bf16_f32 v213, v18, v19
	v_cvt_pk_fp8_f32 v217, v16, v17
	v_cvt_pk_fp8_f32 v214, v6, v7 op_sel:[0,0,1]
	v_cvt_pk_fp8_f32 v215, v10, v11 op_sel:[0,0,1]
	v_cvt_pk_fp8_f32 v216, v14, v15 op_sel:[0,0,1]
	v_cvt_pk_fp8_f32 v217, v18, v19 op_sel:[0,0,1]
	s_nop 1
	global_store_dwordx2 v2, v[206:207], s[16:17] nt
	global_store_dwordx2 v2, v[208:209], s[16:17] offset:512 nt
	global_store_dwordx2 v2, v[210:211], s[16:17] offset:1024 nt
	global_store_dwordx2 v2, v[212:213], s[16:17] offset:1536 nt
	global_store_dword v3, v214, s[18:19] nt
	global_store_dword v3, v215, s[18:19] offset:256 nt
	global_store_dword v3, v216, s[18:19] offset:512 nt
	global_store_dword v3, v217, s[18:19] offset:768 nt
	s_add_u32 s16, s16, 0x400000
	s_addc_u32 s17, s17, 0
	s_add_u32 s18, s18, 0x200000
	s_addc_u32 s19, s19, 0
